# attention: K-first DMA order, vmcnt(2) before the tile barrier so V half stays in flight; drain+barrier in exit shim
# speedup vs baseline: 1.0016x; 1.0016x over previous
; __device__ __forceinline__ void partialSM_fix(f32x16& p0) { for (int r = 0; r < 16; ++r) p0[r] = __builtin_amdgcn_exp2f(p0[r]); }
; __device__ __forceinline__ int v_st(int k, int c) { const int kk = (k & ~0xC) | ((k & 4) << 1) | ((k & 8) >> 1); return ((kk >> 3) * 4 + (c >> 5)) * 512 + ((kk & 7) * 32 + (c & 31)) * 2; }
; __device__ __forceinline__ int v_rd_base(int lane) { return ((lane & 3) << 3) | (((lane >> 2) & 3) << 6) | (((lane >> 4) & 1) << 5) | (((lane >> 5) & 1) << 8); }
; #define SLOAD(i, k0) do { sr_[i].vs0 = St::ld8(&Vh[(long)((k0) + sr) * LDK + sc]); sr_[i].vs1 = St::ld8(&Vh[(long)((k0) + 32 + sr) * LDK + sc]); \
;     sr_[i].ks0 = St::ld8(&Kh[(long)((k0) + sr) * LDK + sc]); sr_[i].ks1 = St::ld8(&Kh[(long)((k0) + 32 + sr) * LDK + sc]); } while (0)
; #define SWAIT() do { if constexpr (SDEPTH == 2) asm volatile("s_waitcnt vmcnt(4)" ::: "memory"); else asm volatile("s_waitcnt vmcnt(0)" ::: "memory"); } while (0)
; template <typename TQ>
; __device__ __forceinline__ void attn_dense_body(const TQ* __restrict__ Qb, const bf16* __restrict__ Kh, const bf16* __restrict__ Vh,
;                                                 bf16* __restrict__ Ob, int seq, char* lds) {
;     ...
;   const int tid = threadIdx.x, wid = tid >> 6, lane = tid & 63, r32 = lane & 31, hi = lane >> 5;
;   bf16* V_lds = (bf16*)lds; bf16* K_lds = (bf16*)(lds + 3 * SHM_V);
;   float* ws = (float*)(lds + 3 * SHM_V + 3 * SHM_K) + wid * 64; float* li_l = ws;
;     float l_reg = 0; f32x16 o[4] = {}; bf16x8 qr[8];
;   const TQ* Qw = Qb + (long)(wid * QBLK + r32) * LDQ + hi * 8;
; #pragma unroll
;   for (int d0 = 0; d0 < 8; ++d0) qr[d0] = SQ::tobf(SQ::ld8(Qw + d0 * 16));
;   const int sr = tid >> 4, sc = (tid & 15) * 8, vst0 = v_st(sr, sc), vst1 = v_st(32 + sr, sc);
;   const int vb0 = (int)(uintptr_t)V_lds + v_rd_base(lane);
;   struct { typename St::T vs0, vs1, ks0, ks1; } sr_[SDEPTH];
;     ...
;   f32x16 pA0, pA1, pB0, pB1; constexpr float alA = 1.f, alB = 1.f; bf16x8 pa0, pa1, pa2, pa3; const int NT = seq / KVBLK;
;   constexpr int SE = 0, SO = 0;
;   SLOAD(SE, 0); asm volatile("s_waitcnt vmcnt(0)" ::: "memory"); SWRITE(0, SE);
;   SLOAD(SO, KVBLK);
;   __syncthreads();
;   qkt(pA0, pA1, K_lds, qr, r32, hi); partialSM_fix(pA0);
;   SWAIT(); SWRITE(1, SO); SLOAD(SE, 2 * KVBLK);
;   __syncthreads();
.LBB0_1089:
	s_ashr_i32 s13, s12, 31
	s_lshl_b64 s[18:19], s[12:13], 12
	s_add_u32 s0, s40, s18
	s_addc_u32 s9, s41, s19
	s_lshl_b32 s52, s8, 7
	s_lshl_b32 s18, s8, 8
	s_add_u32 s54, s0, s18
	s_addc_u32 s55, s9, 0
	s_lshr_b32 s0, s8, 1
	s_lshl_b64 s[8:9], s[0:1], 22
	s_add_u32 s8, s8, s14
	s_addc_u32 s9, s9, s15
	s_lshl_b64 s[8:9], s[8:9], 1
	s_add_u32 s18, s3, s8
	s_addc_u32 s19, s38, s9
	s_add_u32 s20, s39, s8
	s_addc_u32 s21, s42, s9
	global_load_dwordx4 v[0:3], v192, s[20:21]
	global_load_dwordx4 v[4:7], v193, s[20:21]
	global_load_dwordx4 v[8:11], v192, s[18:19]
	global_load_dwordx4 v[12:15], v193, s[18:19]
	v_lshl_add_u64 v[16:17], s[54:55], 0, v[170:171]
	v_lshl_add_u64 v[16:17], v[16:17], 0, v[172:173]
	global_load_dwordx4 v[140:143], v[16:17], off
	global_load_dwordx4 v[136:139], v[16:17], off offset:32
	global_load_dwordx4 v[132:135], v[16:17], off offset:64
	global_load_dwordx4 v[128:131], v[16:17], off offset:96
	global_load_dwordx4 v[124:127], v[16:17], off offset:128
	global_load_dwordx4 v[120:123], v[16:17], off offset:160
	global_load_dwordx4 v[116:119], v[16:17], off offset:192
	global_load_dwordx4 v[112:115], v[16:17], off offset:224
	s_waitcnt vmcnt(0)
	global_load_dwordx4 v[50:53], v198, s[20:21]
	global_load_dwordx4 v[54:57], v198, s[18:19]
	global_load_dwordx4 v[58:61], v199, s[20:21]
	global_load_dwordx4 v[96:99], v199, s[18:19]
	v_add_u32_e32 v33, 0, v190
	v_add_u32_e32 v30, 0, v188
	v_add_u32_e32 v31, 0, v189
	s_lshl_b64 s[8:9], s[0:1], 23
	s_lshl_b64 s[14:15], s[14:15], 1
	s_add_u32 s8, s8, s14
	v_add_u32_e32 v62, s45, v180
	v_add_u32_e32 v63, s45, v181
	v_mov_b32_e32 v169, 0
	s_addc_u32 s9, s9, s15
	s_mov_b32 s54, 1
	s_mov_b32 s57, 0
	s_mov_b32 s56, 2
	s_mov_b32 s55, 4
	v_mov_b32_e32 v16, 0
	v_mov_b32_e32 v32, 0
	v_mov_b32_e32 v48, 0
	v_mov_b32_e32 v17, v169
	v_mov_b32_e32 v38, v169
	v_mov_b32_e32 v39, v169
	v_mov_b32_e32 v44, v169
	v_mov_b32_e32 v45, v169
	v_mov_b32_e32 v46, v169
	v_mov_b32_e32 v47, v169
	v_mov_b32_e32 v49, v169
	v_lshl_add_u64 v[174:175], v[166:167], 0, s[8:9]
	s_waitcnt vmcnt(15)
	ds_write_b128 v194, v[0:3]
	s_waitcnt vmcnt(14)
	ds_write_b128 v195, v[4:7]
	s_waitcnt vmcnt(13)
	ds_write_b128 v196, v[8:11] offset:49152
	s_waitcnt vmcnt(12)
	ds_write_b128 v197, v[12:15] offset:49152
	s_waitcnt lgkmcnt(0)
	s_barrier
	ds_read_b128 v[0:3], v200 offset:49152
	ds_read_b128 v[4:7], v200 offset:57344
	s_waitcnt vmcnt(11) lgkmcnt(1)
	v_mfma_f32_32x32x16_bf16 v[80:95], v[0:3], v[140:143], 0
	v_mov_b32_e32 v8, v169
	v_mov_b32_e32 v9, v169
	v_mov_b32_e32 v14, v169
	v_mov_b32_e32 v15, v169
	s_waitcnt lgkmcnt(0)
	v_mfma_f32_32x32x16_bf16 v[64:79], v[4:7], v[140:143], 0
	ds_read_b128 v[0:3], v201 offset:49152
	ds_read_b128 v[4:7], v201 offset:57344
	ds_read_b128 v[10:13], v203 offset:49152
	ds_read_b128 v[18:21], v203 offset:57344
	ds_read_b128 v[22:25], v204 offset:49152
	s_waitcnt vmcnt(10) lgkmcnt(4)
	v_mfma_f32_32x32x16_bf16 v[80:95], v[0:3], v[136:139], v[80:95]
	ds_read_b128 v[0:3], v202 offset:49152
	s_waitcnt lgkmcnt(4)
	v_mfma_f32_32x32x16_bf16 v[64:79], v[4:7], v[136:139], v[64:79]
	ds_read_b128 v[4:7], v202 offset:57344
	s_waitcnt vmcnt(9) lgkmcnt(0)
	v_mfma_f32_32x32x16_bf16 v[64:79], v[4:7], v[132:135], v[64:79]
	v_mov_b32_e32 v4, v169
	v_mov_b32_e32 v5, v169
	v_mov_b32_e32 v6, v169
	v_mov_b32_e32 v7, v169
	s_waitcnt vmcnt(8)
	v_mfma_f32_32x32x16_bf16 v[64:79], v[18:21], v[128:131], v[64:79]
	ds_read_b128 v[18:21], v204 offset:57344
	ds_read_b128 v[26:29], v30 offset:49152
	ds_read_b128 v[34:37], v30 offset:57344
	ds_read_b128 v[40:43], v31 offset:49152
	ds_read_b128 v[100:103], v31 offset:57344
	ds_read_b128 v[104:107], v33 offset:49152
	ds_read_b128 v[108:111], v33 offset:57344
	s_waitcnt vmcnt(0)
	global_load_dwordx4 v[144:147], v205, s[20:21]
	global_load_dwordx4 v[152:155], v205, s[18:19]
	global_load_dwordx4 v[148:151], v206, s[20:21]
	global_load_dwordx4 v[156:159], v206, s[18:19]
	v_mov_b32_e32 v30, v169
	v_mov_b32_e32 v31, v169
	v_mov_b32_e32 v33, v169
	v_mfma_f32_32x32x16_bf16 v[80:95], v[0:3], v[132:135], v[80:95]
	v_mov_b32_e32 v0, 0
	v_mov_b32_e32 v1, v169
	v_mov_b32_e32 v2, v169
	v_mov_b32_e32 v3, v169
	s_waitcnt vmcnt(7)
	ds_write_b128 v194, v[50:53] offset:16384
	s_waitcnt vmcnt(5)
	ds_write_b128 v195, v[58:61] offset:16384
	ds_write_b128 v62, v[54:57]
	s_waitcnt vmcnt(4)
	ds_write_b128 v63, v[96:99]
	v_mov_b32_e32 v50, v169
	v_mov_b32_e32 v51, v169
	v_mfma_f32_32x32x16_bf16 v[80:95], v[10:13], v[128:131], v[80:95]
	v_mov_b32_e32 v10, v169
	v_mov_b32_e32 v11, v169
	v_mov_b32_e32 v12, v169
	v_mov_b32_e32 v13, v169
	v_mov_b32_e32 v52, v169
	v_mov_b32_e32 v53, v169
	v_mov_b32_e32 v54, v169
	v_mfma_f32_32x32x16_bf16 v[80:95], v[22:25], v[124:127], v[80:95]
	v_mov_b32_e32 v22, v169
	v_mov_b32_e32 v23, v169
	v_mov_b32_e32 v24, v169
	v_mov_b32_e32 v25, v169
	v_mov_b32_e32 v55, v169
	v_mov_b32_e32 v56, v169
	v_mov_b32_e32 v57, v169
	s_waitcnt lgkmcnt(10)
	v_mfma_f32_32x32x16_bf16 v[64:79], v[18:21], v[124:127], v[64:79]
	v_mov_b32_e32 v18, v169
	v_mov_b32_e32 v19, v169
	v_mov_b32_e32 v20, v169
	v_mov_b32_e32 v21, v169
	v_mov_b32_e32 v58, v169
	v_mov_b32_e32 v59, v169
	v_mov_b32_e32 v60, v169
	s_waitcnt lgkmcnt(9)
	v_mfma_f32_32x32x16_bf16 v[80:95], v[26:29], v[120:123], v[80:95]
	v_mov_b32_e32 v26, v169
	v_mov_b32_e32 v27, v169
	v_mov_b32_e32 v28, v169
	v_mov_b32_e32 v29, v169
	v_mov_b32_e32 v61, v169
	v_mov_b32_e32 v62, v169
	v_mov_b32_e32 v63, v169
	s_waitcnt lgkmcnt(8)
	v_mfma_f32_32x32x16_bf16 v[64:79], v[34:37], v[120:123], v[64:79]
	v_mov_b32_e32 v34, v169
	v_mov_b32_e32 v35, v169
	v_mov_b32_e32 v36, v169
	v_mov_b32_e32 v37, v169
	s_waitcnt lgkmcnt(0)
	s_barrier
; #define SBAR() __builtin_amdgcn_sched_barrier(0)
; __device__ __forceinline__ void partialSM_fix(f32x16& p0) { for (int r = 0; r < 16; ++r) p0[r] = __builtin_amdgcn_exp2f(p0[r]); }
; #define SLOAD(i, k0) do { sr_[i].vs0 = St::ld8(&Vh[(long)((k0) + sr) * LDK + sc]); sr_[i].vs1 = St::ld8(&Vh[(long)((k0) + 32 + sr) * LDK + sc]); \
;     sr_[i].ks0 = St::ld8(&Kh[(long)((k0) + sr) * LDK + sc]); sr_[i].ks1 = St::ld8(&Kh[(long)((k0) + 32 + sr) * LDK + sc]); } while (0)
; #define SWAIT() do { if constexpr (SDEPTH == 2) asm volatile("s_waitcnt vmcnt(4)" ::: "memory"); else asm volatile("s_waitcnt vmcnt(0)" ::: "memory"); } while (0)
; template <typename TQ>
; __device__ __forceinline__ void attn_dense_body(const TQ* __restrict__ Qb, const bf16* __restrict__ Kh, const bf16* __restrict__ Vh,
;                                                 bf16* __restrict__ Ob, int seq, char* lds) {
;     ...
;   qkt(pA0, pA1, K_lds, qr, r32, hi); partialSM_fix(pA0);
;   SWAIT(); SWRITE(1, SO); SLOAD(SE, 2 * KVBLK);
;   __syncthreads();
;   int prev = 0, cur = 1, next = 2;
;   for (int j = 1; j + 1 < NT; j += 2) {
;     SBAR(); qkt(pB0, pB1, (bf16*)((char*)K_lds + cur * (int)SHM_K), qr, r32, hi);
;     finishSM(pA0, pA1, alA, l_reg, pa0, pa1, pa2, pa3); SBAR();
;     SWAIT(); SWRITE(next, SE);
;     if (j + 2 < NT) SLOAD(SO, (j + 2) * KVBLK); SBAR();
;     pv_d0(o, vb0 + prev * (int)SHM_V, pa0, pa1, pa2, pa3); partialSM_fix(pB0);
;     __syncthreads();
;     { const int t_ = prev; prev = cur; cur = next; next = t_; }
;     SBAR(); qkt(pA0, pA1, (bf16*)((char*)K_lds + cur * (int)SHM_K), qr, r32, hi);
;     finishSM(pB0, pB1, alB, l_reg, pa0, pa1, pa2, pa3); SBAR();
	v_mfma_f32_32x32x16_bf16 v[80:95], v[40:43], v[116:119], v[80:95]
	v_mov_b32_e32 v40, v169
	v_mov_b32_e32 v41, v169
	v_mov_b32_e32 v42, v169
	v_mov_b32_e32 v43, v169
	v_mfma_f32_32x32x16_bf16 v[64:79], v[100:103], v[116:119], v[64:79]
	v_mfma_f32_32x32x16_bf16 v[80:95], v[104:107], v[112:115], v[80:95]
	v_mfma_f32_32x32x16_bf16 v[64:79], v[108:111], v[112:115], v[64:79]
	s_nop 10
	v_exp_f32_e32 v224, v80
	v_exp_f32_e32 v225, v81
	v_exp_f32_e32 v226, v82
	v_exp_f32_e32 v227, v83
	v_exp_f32_e32 v228, v84
	v_exp_f32_e32 v229, v85
	v_exp_f32_e32 v230, v86
	v_exp_f32_e32 v231, v87
	v_exp_f32_e32 v232, v88
	v_exp_f32_e32 v233, v89
	v_exp_f32_e32 v234, v90
	v_exp_f32_e32 v235, v91
	v_exp_f32_e32 v236, v92
	v_exp_f32_e32 v237, v93
	v_exp_f32_e32 v238, v94
	v_exp_f32_e32 v239, v95
	s_waitcnt vmcnt(0)
	v_add_u32_e32 v144, 0xc000, v183
	v_add_u32_e32 v145, 0xc000, v184
	v_add_u32_e32 v146, 0xc000, v185
	v_add_u32_e32 v147, 0xc000, v186
	v_add_u32_e32 v148, 0xc000, v187
	v_add_u32_e32 v149, 0xc000, v188
	v_add_u32_e32 v150, 0xc000, v189
	v_add_u32_e32 v151, 0xc000, v190
	s_add_i32 s32, s53, 2
	s_add_u32 s90, s39, s8
	s_addc_u32 s91, s42, s9
	s_add_u32 s92, s3, s8
	s_addc_u32 s93, s38, s9
	s_add_u32 s90, s90, 0x8000
	s_addc_u32 s91, s91, 0
	s_add_u32 s92, s92, 0x8000
	s_addc_u32 s93, s93, 0
	v_readfirstlane_b32 s80, v160
	v_lshrrev_b32_e32 v248, 5, v162
	s_nop 3
	s_lshr_b32 s80, s80, 6
	s_lshl_b32 s80, s80, 11
	s_add_i32 s81, s80, 0x400
	s_add_i32 s82, s80, 0xc000
	s_add_i32 s83, s80, 0xc400
	v_and_b32_e32 v249, 31, v176
	v_lshrrev_b32_e32 v249, 2, v249
	v_lshl_add_u32 v249, v249, 8, v248
	v_lshrrev_b32_e32 v174, 5, v176
	v_lshl_add_u32 v249, v174, 6, v249
	v_and_b32_e32 v174, 3, v176
	v_lshl_add_u32 v249, v174, 4, v249
	v_lshrrev_b32_e32 v174, 4, v176
	v_lshrrev_b32_e32 v175, 16, v162
	v_and_b32_e32 v175, 1, v175
	v_lshl_or_b32 v175, v175, 3, v174
	v_and_b32_e32 v250, 15, v176
	v_xor_b32_e32 v175, v250, v175
	v_lshl_add_u32 v248, v174, 8, v248
	v_lshl_add_u32 v174, v175, 4, v248
	v_xor_b32_e32 v175, 64, v174
	v_add_u32_e32 v175, 0x400, v175
	v_add_u32_e32 v248, 0x80, v249
	s_add_i32 m0, s82, 0x8000
	s_nop 0
	global_load_lds_dwordx4 v174, s[92:93]
	s_add_i32 m0, s83, 0x8000
	s_nop 0
	global_load_lds_dwordx4 v175, s[92:93]
	s_add_u32 s92, s92, 0x4000
	s_addc_u32 s93, s93, 0
	s_add_i32 m0, s80, 0x8000
	s_add_u32 s96, s90, 0x80
	s_addc_u32 s97, s91, 0
	global_load_lds_dwordx4 v249, s[90:91]
	s_add_i32 m0, s81, 0x8000
	s_nop 0
	global_load_lds_dwordx4 v249, s[96:97]
	s_add_u32 s90, s90, 0x4000
	s_addc_u32 s91, s91, 0
	v_add_f32_e32 v254, v224, v226
	v_add_f32_e32 v255, v225, v227
	v_add_f32_e32 v254, v254, v228
	v_add_f32_e32 v255, v255, v229
	v_add_f32_e32 v254, v254, v230
	v_add_f32_e32 v255, v255, v231
	v_add_f32_e32 v254, v254, v232
	v_add_f32_e32 v255, v255, v233
	v_add_f32_e32 v254, v254, v234
	v_add_f32_e32 v255, v255, v235
	v_add_f32_e32 v254, v254, v236
	v_add_f32_e32 v255, v255, v237
	v_add_f32_e32 v254, v254, v238
	v_add_f32_e32 v255, v255, v239
	v_add_f32_e32 v254, v254, v255
	s_waitcnt lgkmcnt(0)
	ds_read_b128 v[208:211], v144 offset:16384
	ds_read_b128 v[212:215], v144 offset:24576
	ds_read_b128 v[216:219], v145 offset:16384
	ds_read_b128 v[220:223], v145 offset:24576
	ds_read_b128 v[240:243], v146 offset:16384
	ds_read_b128 v[244:247], v146 offset:24576
.Latt_loop:
	s_waitcnt lgkmcnt(4)
	v_mfma_f32_32x32x16_bf16 v[96:111], v[208:211], v[140:143], 0
	v_exp_f32_e32 v64, v64
	v_exp_f32_e32 v65, v65
	v_cvt_pk_bf16_f32 v224, v224, v225
	v_mfma_f32_32x32x16_bf16 v[80:95], v[212:215], v[140:143], 0
	ds_read_b128 v[208:211], v147 offset:16384
	ds_read_b128 v[212:215], v147 offset:24576
	v_exp_f32_e32 v66, v66
	v_exp_f32_e32 v67, v67
	v_cvt_pk_bf16_f32 v225, v226, v227
	s_waitcnt lgkmcnt(4)
	v_mfma_f32_32x32x16_bf16 v[96:111], v[216:219], v[136:139], v[96:111]
	v_exp_f32_e32 v68, v68
	v_exp_f32_e32 v69, v69
	v_cvt_pk_bf16_f32 v226, v228, v229
	v_mfma_f32_32x32x16_bf16 v[80:95], v[220:223], v[136:139], v[80:95]
	ds_read_b128 v[216:219], v148 offset:16384
	ds_read_b128 v[220:223], v148 offset:24576
	v_exp_f32_e32 v70, v70
	v_exp_f32_e32 v71, v71
	v_cvt_pk_bf16_f32 v227, v230, v231
	v_add_f32_e32 v251, v64, v66
	s_waitcnt lgkmcnt(4)
	v_mfma_f32_32x32x16_bf16 v[96:111], v[240:243], v[132:135], v[96:111]
	v_exp_f32_e32 v72, v72
	v_exp_f32_e32 v73, v73
	v_add_f32_e32 v253, v65, v67
	v_mfma_f32_32x32x16_bf16 v[80:95], v[244:247], v[132:135], v[80:95]
	ds_read_b128 v[240:243], v149 offset:16384
	ds_read_b128 v[244:247], v149 offset:24576
	v_exp_f32_e32 v74, v74
	v_exp_f32_e32 v75, v75
	v_add_f32_e32 v251, v251, v68
	s_waitcnt lgkmcnt(4)
	v_mfma_f32_32x32x16_bf16 v[96:111], v[208:211], v[128:131], v[96:111]
	v_exp_f32_e32 v76, v76
	v_exp_f32_e32 v77, v77
	v_add_f32_e32 v253, v253, v69
	v_cvt_pk_bf16_f32 v228, v232, v233
	v_mfma_f32_32x32x16_bf16 v[80:95], v[212:215], v[128:131], v[80:95]
	ds_read_b128 v[208:211], v150 offset:16384
	ds_read_b128 v[212:215], v150 offset:24576
	v_exp_f32_e32 v78, v78
	v_exp_f32_e32 v79, v79
	v_add_f32_e32 v251, v251, v70
	v_cvt_pk_bf16_f32 v229, v234, v235
	s_waitcnt lgkmcnt(4)
	v_mfma_f32_32x32x16_bf16 v[96:111], v[216:219], v[124:127], v[96:111]
	v_add_f32_e32 v253, v253, v71
	v_cvt_pk_bf16_f32 v230, v236, v237
	v_cvt_pk_bf16_f32 v231, v238, v239
	v_add_f32_e32 v251, v251, v72
	v_mfma_f32_32x32x16_bf16 v[80:95], v[220:223], v[124:127], v[80:95]
	ds_read_b128 v[216:219], v151 offset:16384
	ds_read_b128 v[220:223], v151 offset:24576
	v_add_f32_e32 v253, v253, v73
	v_cvt_pk_bf16_f32 v232, v64, v65
	v_cvt_pk_bf16_f32 v233, v66, v67
	s_waitcnt lgkmcnt(4)
; #define SBAR() __builtin_amdgcn_sched_barrier(0)
; __device__ __forceinline__ void partialSM_fix(f32x16& p0) { for (int r = 0; r < 16; ++r) p0[r] = __builtin_amdgcn_exp2f(p0[r]); }
; #define SLOAD(i, k0) do { sr_[i].vs0 = St::ld8(&Vh[(long)((k0) + sr) * LDK + sc]); sr_[i].vs1 = St::ld8(&Vh[(long)((k0) + 32 + sr) * LDK + sc]); \
;     sr_[i].ks0 = St::ld8(&Kh[(long)((k0) + sr) * LDK + sc]); sr_[i].ks1 = St::ld8(&Kh[(long)((k0) + 32 + sr) * LDK + sc]); } while (0)
; template <int D0> __device__ __forceinline__ void pv_one(f32x16& od, int vb, bf16x8 pa0, bf16x8 pa1, bf16x8 pa2, bf16x8 pa3) {
;   const s16x4 l0 = tr_read<v_rd_off(D0, 0, 0)>(vb), h0 = tr_read<v_rd_off(D0, 0, 1)>(vb), l1 = tr_read<v_rd_off(D0, 1, 0)>(vb), h1 = tr_read<v_rd_off(D0, 1, 1)>(vb);
;   const s16x4 l2 = tr_read<v_rd_off(D0, 2, 0)>(vb), h2 = tr_read<v_rd_off(D0, 2, 1)>(vb), l3 = tr_read<v_rd_off(D0, 3, 0)>(vb), h3 = tr_read<v_rd_off(D0, 3, 1)>(vb);
;   asm volatile("s_waitcnt lgkmcnt(0)" ::: "memory"); SBAR();
;     ...
;   od = __builtin_amdgcn_mfma_f32_32x32x16_bf16(pa0, PK(l0, h0), od, 0, 0, 0);
;   od = __builtin_amdgcn_mfma_f32_32x32x16_bf16(pa1, PK(l1, h1), od, 0, 0, 0);
;   od = __builtin_amdgcn_mfma_f32_32x32x16_bf16(pa2, PK(l2, h2), od, 0, 0, 0);
;   od = __builtin_amdgcn_mfma_f32_32x32x16_bf16(pa3, PK(l3, h3), od, 0, 0, 0);
;     ...
; }
; __device__ __forceinline__ void pv_d0(f32x16* o, int vb, bf16x8 pa0, bf16x8 pa1, bf16x8 pa2, bf16x8 pa3) {
;   pv_one<0>(o[0], vb, pa0, pa1, pa2, pa3); pv_one<1>(o[1], vb, pa0, pa1, pa2, pa3); pv_one<2>(o[2], vb, pa0, pa1, pa2, pa3); pv_one<3>(o[3], vb, pa0, pa1, pa2, pa3);
; template <typename TQ>
; __device__ __forceinline__ void attn_dense_body(const TQ* __restrict__ Qb, const bf16* __restrict__ Kh, const bf16* __restrict__ Vh,
;                                                 bf16* __restrict__ Ob, int seq, char* lds) {
;     ...
;   for (int j = 1; j + 1 < NT; j += 2) {
;     SBAR(); qkt(pB0, pB1, (bf16*)((char*)K_lds + cur * (int)SHM_K), qr, r32, hi);
;     finishSM(pA0, pA1, alA, l_reg, pa0, pa1, pa2, pa3); SBAR();
;     SWAIT(); SWRITE(next, SE);
;     if (j + 2 < NT) SLOAD(SO, (j + 2) * KVBLK); SBAR();
;     pv_d0(o, vb0 + prev * (int)SHM_V, pa0, pa1, pa2, pa3); partialSM_fix(pB0);
;     __syncthreads();
	v_mfma_f32_32x32x16_bf16 v[96:111], v[240:243], v[120:123], v[96:111]
	v_add_f32_e32 v251, v251, v74
	v_cvt_pk_bf16_f32 v234, v68, v69
	v_cvt_pk_bf16_f32 v235, v70, v71
	v_mfma_f32_32x32x16_bf16 v[80:95], v[244:247], v[120:123], v[80:95]
	ds_read_b64_tr_b16 v[240:241], v179 offset:0
	ds_read_b64_tr_b16 v[242:243], v179 offset:2048
	ds_read_b64_tr_b16 v[244:245], v179 offset:4096
	ds_read_b64_tr_b16 v[246:247], v179 offset:6144
	v_add_f32_e32 v253, v253, v75
	v_add_f32_e32 v251, v251, v76
	v_cvt_pk_bf16_f32 v236, v72, v73
	v_cvt_pk_bf16_f32 v237, v74, v75
	s_waitcnt lgkmcnt(6)
	v_mfma_f32_32x32x16_bf16 v[96:111], v[208:211], v[116:119], v[96:111]
	v_add_f32_e32 v253, v253, v77
	v_add_f32_e32 v251, v251, v78
	v_mfma_f32_32x32x16_bf16 v[80:95], v[212:215], v[116:119], v[80:95]
	ds_read_b64_tr_b16 v[208:209], v179 offset:8192
	ds_read_b64_tr_b16 v[210:211], v179 offset:10240
	ds_read_b64_tr_b16 v[212:213], v179 offset:12288
	ds_read_b64_tr_b16 v[214:215], v179 offset:14336
	v_add_f32_e32 v253, v253, v79
	v_cvt_pk_bf16_f32 v238, v76, v77
	v_cvt_pk_bf16_f32 v239, v78, v79
	s_waitcnt lgkmcnt(8)
	v_mfma_f32_32x32x16_bf16 v[96:111], v[216:219], v[112:115], v[96:111]
	v_add_f32_e32 v251, v251, v253
	v_add_f32_e32 v254, v254, v251
	v_mfma_f32_32x32x16_bf16 v[80:95], v[220:223], v[112:115], v[80:95]
	ds_read_b64_tr_b16 v[216:217], v179 offset:512
	ds_read_b64_tr_b16 v[218:219], v179 offset:2560
	ds_read_b64_tr_b16 v[220:221], v179 offset:4608
	ds_read_b64_tr_b16 v[222:223], v179 offset:6656
	v_add_f32_e32 v169, v169, v254
	s_waitcnt lgkmcnt(8)
	v_mfma_f32_32x32x16_bf16 v[0:15], v[224:227], v[240:243], v[0:15]
	ds_read_b64_tr_b16 v[64:65], v179 offset:8704
	ds_read_b64_tr_b16 v[66:67], v179 offset:10752
	v_mfma_f32_32x32x16_bf16 v[0:15], v[228:231], v[244:247], v[0:15]
	ds_read_b64_tr_b16 v[68:69], v179 offset:12800
	ds_read_b64_tr_b16 v[70:71], v179 offset:14848
	v_exp_f32_e32 v96, v96
	v_exp_f32_e32 v97, v97
	s_waitcnt lgkmcnt(8)
	v_mfma_f32_32x32x16_bf16 v[0:15], v[232:235], v[208:211], v[0:15]
	ds_read_b64_tr_b16 v[72:73], v179 offset:1024
	ds_read_b64_tr_b16 v[74:75], v179 offset:3072
	v_exp_f32_e32 v98, v98
	v_exp_f32_e32 v99, v99
	v_mfma_f32_32x32x16_bf16 v[0:15], v[236:239], v[212:215], v[0:15]
	ds_read_b64_tr_b16 v[76:77], v179 offset:5120
	ds_read_b64_tr_b16 v[78:79], v179 offset:7168
	v_exp_f32_e32 v100, v100
	v_exp_f32_e32 v101, v101
	v_add_f32_e32 v254, v96, v98
	s_waitcnt lgkmcnt(8)
	v_mfma_f32_32x32x16_bf16 v[16:31], v[224:227], v[216:219], v[16:31]
	ds_read_b64_tr_b16 v[240:241], v179 offset:9216
	ds_read_b64_tr_b16 v[242:243], v179 offset:11264
	v_exp_f32_e32 v102, v102
	v_exp_f32_e32 v103, v103
	v_add_f32_e32 v255, v97, v99
	v_mfma_f32_32x32x16_bf16 v[16:31], v[228:231], v[220:223], v[16:31]
	ds_read_b64_tr_b16 v[244:245], v179 offset:13312
	ds_read_b64_tr_b16 v[246:247], v179 offset:15360
	v_exp_f32_e32 v104, v104
	v_exp_f32_e32 v105, v105
	v_add_f32_e32 v254, v254, v100
	s_waitcnt lgkmcnt(8)
	v_mfma_f32_32x32x16_bf16 v[16:31], v[232:235], v[64:67], v[16:31]
	ds_read_b64_tr_b16 v[64:65], v179 offset:1536
	ds_read_b64_tr_b16 v[66:67], v179 offset:3584
	v_exp_f32_e32 v106, v106
	v_exp_f32_e32 v107, v107
	v_add_f32_e32 v255, v255, v101
	v_mfma_f32_32x32x16_bf16 v[16:31], v[236:239], v[68:71], v[16:31]
	ds_read_b64_tr_b16 v[68:69], v179 offset:5632
	ds_read_b64_tr_b16 v[70:71], v179 offset:7680
	v_exp_f32_e32 v108, v108
	v_exp_f32_e32 v109, v109
	v_add_f32_e32 v254, v254, v102
	s_waitcnt lgkmcnt(8)
	v_mfma_f32_32x32x16_bf16 v[32:47], v[224:227], v[72:75], v[32:47]
	ds_read_b64_tr_b16 v[72:73], v179 offset:9728
	ds_read_b64_tr_b16 v[74:75], v179 offset:11776
	v_exp_f32_e32 v110, v110
	v_exp_f32_e32 v111, v111
	v_add_f32_e32 v255, v255, v103
	v_mfma_f32_32x32x16_bf16 v[32:47], v[228:231], v[76:79], v[32:47]
	ds_read_b64_tr_b16 v[76:77], v179 offset:13824
	ds_read_b64_tr_b16 v[78:79], v179 offset:15872
	v_add_f32_e32 v254, v254, v104
	v_add_f32_e32 v255, v255, v105
	v_add_f32_e32 v254, v254, v106
	s_waitcnt lgkmcnt(8)
	v_mfma_f32_32x32x16_bf16 v[32:47], v[232:235], v[240:243], v[32:47]
	v_add_f32_e32 v255, v255, v107
	v_add_f32_e32 v254, v254, v108
	v_add_f32_e32 v255, v255, v109
	v_mfma_f32_32x32x16_bf16 v[32:47], v[236:239], v[244:247], v[32:47]
	v_add_f32_e32 v254, v254, v110
	v_add_f32_e32 v255, v255, v111
	s_waitcnt vmcnt(2)
	s_waitcnt lgkmcnt(0)
	s_barrier
; #define SBAR() __builtin_amdgcn_sched_barrier(0)
; __device__ __forceinline__ void partialSM_fix(f32x16& p0) { for (int r = 0; r < 16; ++r) p0[r] = __builtin_amdgcn_exp2f(p0[r]); }
; #define SLOAD(i, k0) do { sr_[i].vs0 = St::ld8(&Vh[(long)((k0) + sr) * LDK + sc]); sr_[i].vs1 = St::ld8(&Vh[(long)((k0) + 32 + sr) * LDK + sc]); \
;     sr_[i].ks0 = St::ld8(&Kh[(long)((k0) + sr) * LDK + sc]); sr_[i].ks1 = St::ld8(&Kh[(long)((k0) + 32 + sr) * LDK + sc]); } while (0)
; #define SWAIT() do { if constexpr (SDEPTH == 2) asm volatile("s_waitcnt vmcnt(4)" ::: "memory"); else asm volatile("s_waitcnt vmcnt(0)" ::: "memory"); } while (0)
; __device__ __forceinline__ void qkt(f32x16& p0, f32x16& p1, const bf16* Ks, const bf16x8* qr, int r32, int hi) {
;   p0 = f32x16{}; p1 = f32x16{};
;   for (int d0 = 0; d0 < 8; ++d0) { int cb = (d0 * 16 + hi * 8) * 2;
;     bf16x8 b0 = *reinterpret_cast<const bf16x8*>((const char*)Ks + KSWZ(r32, cb));
;     bf16x8 b1 = *reinterpret_cast<const bf16x8*>((const char*)Ks + KSWZ(32 + r32, cb));
;     p0 = __builtin_amdgcn_mfma_f32_32x32x16_bf16(b0, qr[d0], p0, 0, 0, 0);
;     p1 = __builtin_amdgcn_mfma_f32_32x32x16_bf16(b1, qr[d0], p1, 0, 0, 0); }
; }
; template <typename TQ>
; __device__ __forceinline__ void attn_dense_body(const TQ* __restrict__ Qb, const bf16* __restrict__ Kh, const bf16* __restrict__ Vh,
;                                                 bf16* __restrict__ Ob, int seq, char* lds) {
;     ...
;     SBAR(); qkt(pB0, pB1, (bf16*)((char*)K_lds + cur * (int)SHM_K), qr, r32, hi);
;     finishSM(pA0, pA1, alA, l_reg, pa0, pa1, pa2, pa3); SBAR();
;     SWAIT(); SWRITE(next, SE);
;     if (j + 2 < NT) SLOAD(SO, (j + 2) * KVBLK); SBAR();
;     pv_d0(o, vb0 + prev * (int)SHM_V, pa0, pa1, pa2, pa3); partialSM_fix(pB0);
	ds_read_b128 v[208:211], v144 offset:32768
	ds_read_b128 v[212:215], v144 offset:40960
	ds_read_b128 v[216:219], v145 offset:32768
	ds_read_b128 v[220:223], v145 offset:40960
	ds_read_b128 v[240:243], v146 offset:32768
	ds_read_b128 v[244:247], v146 offset:40960
	v_mfma_f32_32x32x16_bf16 v[48:63], v[224:227], v[64:67], v[48:63]
	v_add_f32_e32 v254, v254, v255
	s_add_i32 m0, s82, 0x0
	s_add_u32 s98, s92, 0x4000
	global_load_lds_dwordx4 v174, s[92:93]
	s_addc_u32 s99, s93, 0
	v_mfma_f32_32x32x16_bf16 v[48:63], v[228:231], v[68:71], v[48:63]
	s_add_i32 m0, s83, 0x0
	s_nop 0
	global_load_lds_dwordx4 v175, s[92:93]
	s_mov_b64 s[92:93], s[98:99]
	v_mfma_f32_32x32x16_bf16 v[48:63], v[232:235], v[72:75], v[48:63]
	s_add_i32 m0, s80, 0x0
	s_add_u32 s96, s90, 0x80
	s_addc_u32 s97, s91, 0
	global_load_lds_dwordx4 v249, s[90:91]
	v_mfma_f32_32x32x16_bf16 v[48:63], v[236:239], v[76:79], v[48:63]
	s_add_i32 m0, s81, 0x0
	s_add_u32 s90, s90, 0x4000
	global_load_lds_dwordx4 v249, s[96:97]
	s_addc_u32 s91, s91, 0
	s_waitcnt lgkmcnt(4)
	v_mfma_f32_32x32x16_bf16 v[224:239], v[208:211], v[140:143], 0
	v_exp_f32_e32 v80, v80
	v_exp_f32_e32 v81, v81
	v_cvt_pk_bf16_f32 v96, v96, v97
	v_mfma_f32_32x32x16_bf16 v[64:79], v[212:215], v[140:143], 0
	ds_read_b128 v[208:211], v147 offset:32768
	ds_read_b128 v[212:215], v147 offset:40960
	v_exp_f32_e32 v82, v82
	v_exp_f32_e32 v83, v83
	v_cvt_pk_bf16_f32 v97, v98, v99
	s_waitcnt lgkmcnt(4)
	v_mfma_f32_32x32x16_bf16 v[224:239], v[216:219], v[136:139], v[224:239]
	v_exp_f32_e32 v84, v84
	v_exp_f32_e32 v85, v85
	v_cvt_pk_bf16_f32 v98, v100, v101
	v_mfma_f32_32x32x16_bf16 v[64:79], v[220:223], v[136:139], v[64:79]
	ds_read_b128 v[216:219], v148 offset:32768
	ds_read_b128 v[220:223], v148 offset:40960
	v_exp_f32_e32 v86, v86
	v_exp_f32_e32 v87, v87
	v_cvt_pk_bf16_f32 v99, v102, v103
	v_add_f32_e32 v251, v80, v82
	s_waitcnt lgkmcnt(4)
	v_mfma_f32_32x32x16_bf16 v[224:239], v[240:243], v[132:135], v[224:239]
	v_exp_f32_e32 v88, v88
	v_exp_f32_e32 v89, v89
	v_add_f32_e32 v253, v81, v83
	v_mfma_f32_32x32x16_bf16 v[64:79], v[244:247], v[132:135], v[64:79]
	ds_read_b128 v[240:243], v149 offset:32768
	ds_read_b128 v[244:247], v149 offset:40960
	v_exp_f32_e32 v90, v90
	v_exp_f32_e32 v91, v91
	v_add_f32_e32 v251, v251, v84
	s_waitcnt lgkmcnt(4)
	v_mfma_f32_32x32x16_bf16 v[224:239], v[208:211], v[128:131], v[224:239]
	v_exp_f32_e32 v92, v92
	v_exp_f32_e32 v93, v93
	v_add_f32_e32 v253, v253, v85
	v_cvt_pk_bf16_f32 v100, v104, v105
	v_mfma_f32_32x32x16_bf16 v[64:79], v[212:215], v[128:131], v[64:79]
	ds_read_b128 v[208:211], v150 offset:32768
	ds_read_b128 v[212:215], v150 offset:40960
	v_exp_f32_e32 v94, v94
	v_exp_f32_e32 v95, v95
	v_add_f32_e32 v251, v251, v86
	v_cvt_pk_bf16_f32 v101, v106, v107
	s_waitcnt lgkmcnt(4)
	v_mfma_f32_32x32x16_bf16 v[224:239], v[216:219], v[124:127], v[224:239]
	v_add_f32_e32 v253, v253, v87
	v_cvt_pk_bf16_f32 v102, v108, v109
	v_cvt_pk_bf16_f32 v103, v110, v111
	v_add_f32_e32 v251, v251, v88
	v_mfma_f32_32x32x16_bf16 v[64:79], v[220:223], v[124:127], v[64:79]
	ds_read_b128 v[216:219], v151 offset:32768
	ds_read_b128 v[220:223], v151 offset:40960
	v_add_f32_e32 v253, v253, v89
	v_cvt_pk_bf16_f32 v104, v80, v81
	v_cvt_pk_bf16_f32 v105, v82, v83
	s_waitcnt lgkmcnt(4)
	v_mfma_f32_32x32x16_bf16 v[224:239], v[240:243], v[120:123], v[224:239]
	v_add_f32_e32 v251, v251, v90
	v_cvt_pk_bf16_f32 v106, v84, v85
	v_cvt_pk_bf16_f32 v107, v86, v87
	v_mfma_f32_32x32x16_bf16 v[64:79], v[244:247], v[120:123], v[64:79]
	ds_read_b64_tr_b16 v[240:241], v179 offset:16384
	ds_read_b64_tr_b16 v[242:243], v179 offset:18432
	ds_read_b64_tr_b16 v[244:245], v179 offset:20480
	ds_read_b64_tr_b16 v[246:247], v179 offset:22528
	v_add_f32_e32 v253, v253, v91
	v_add_f32_e32 v251, v251, v92
	v_cvt_pk_bf16_f32 v108, v88, v89
	v_cvt_pk_bf16_f32 v109, v90, v91
	s_waitcnt lgkmcnt(6)
	v_mfma_f32_32x32x16_bf16 v[224:239], v[208:211], v[116:119], v[224:239]
	v_add_f32_e32 v253, v253, v93
	v_add_f32_e32 v251, v251, v94
	v_mfma_f32_32x32x16_bf16 v[64:79], v[212:215], v[116:119], v[64:79]
	ds_read_b64_tr_b16 v[208:209], v179 offset:24576
	ds_read_b64_tr_b16 v[210:211], v179 offset:26624
	ds_read_b64_tr_b16 v[212:213], v179 offset:28672
	ds_read_b64_tr_b16 v[214:215], v179 offset:30720
	v_add_f32_e32 v253, v253, v95
	v_cvt_pk_bf16_f32 v110, v92, v93
	v_cvt_pk_bf16_f32 v111, v94, v95
	s_waitcnt lgkmcnt(8)
	v_mfma_f32_32x32x16_bf16 v[224:239], v[216:219], v[112:115], v[224:239]
	v_add_f32_e32 v251, v251, v253
	v_add_f32_e32 v254, v254, v251
	v_mfma_f32_32x32x16_bf16 v[64:79], v[220:223], v[112:115], v[64:79]
	ds_read_b64_tr_b16 v[216:217], v179 offset:16896
	ds_read_b64_tr_b16 v[218:219], v179 offset:18944
	ds_read_b64_tr_b16 v[220:221], v179 offset:20992
	ds_read_b64_tr_b16 v[222:223], v179 offset:23040
	v_add_f32_e32 v169, v169, v254
	s_waitcnt lgkmcnt(8)
	v_mfma_f32_32x32x16_bf16 v[0:15], v[96:99], v[240:243], v[0:15]
	ds_read_b64_tr_b16 v[80:81], v179 offset:25088
	ds_read_b64_tr_b16 v[82:83], v179 offset:27136
	v_mfma_f32_32x32x16_bf16 v[0:15], v[100:103], v[244:247], v[0:15]
	ds_read_b64_tr_b16 v[84:85], v179 offset:29184
	ds_read_b64_tr_b16 v[86:87], v179 offset:31232
	v_exp_f32_e32 v224, v224
	v_exp_f32_e32 v225, v225
	s_waitcnt lgkmcnt(8)
	v_mfma_f32_32x32x16_bf16 v[0:15], v[104:107], v[208:211], v[0:15]
	ds_read_b64_tr_b16 v[88:89], v179 offset:17408
	ds_read_b64_tr_b16 v[90:91], v179 offset:19456
	v_exp_f32_e32 v226, v226
	v_exp_f32_e32 v227, v227
	v_mfma_f32_32x32x16_bf16 v[0:15], v[108:111], v[212:215], v[0:15]
	ds_read_b64_tr_b16 v[92:93], v179 offset:21504
	ds_read_b64_tr_b16 v[94:95], v179 offset:23552
	v_exp_f32_e32 v228, v228
	v_exp_f32_e32 v229, v229
	v_add_f32_e32 v254, v224, v226
	s_waitcnt lgkmcnt(8)
; #define SBAR() __builtin_amdgcn_sched_barrier(0)
; __device__ __forceinline__ void partialSM_fix(f32x16& p0) { for (int r = 0; r < 16; ++r) p0[r] = __builtin_amdgcn_exp2f(p0[r]); }
; template <int D0> __device__ __forceinline__ void pv_one(f32x16& od, int vb, bf16x8 pa0, bf16x8 pa1, bf16x8 pa2, bf16x8 pa3) {
;   const s16x4 l0 = tr_read<v_rd_off(D0, 0, 0)>(vb), h0 = tr_read<v_rd_off(D0, 0, 1)>(vb), l1 = tr_read<v_rd_off(D0, 1, 0)>(vb), h1 = tr_read<v_rd_off(D0, 1, 1)>(vb);
;   const s16x4 l2 = tr_read<v_rd_off(D0, 2, 0)>(vb), h2 = tr_read<v_rd_off(D0, 2, 1)>(vb), l3 = tr_read<v_rd_off(D0, 3, 0)>(vb), h3 = tr_read<v_rd_off(D0, 3, 1)>(vb);
;   asm volatile("s_waitcnt lgkmcnt(0)" ::: "memory"); SBAR();
;     ...
;   od = __builtin_amdgcn_mfma_f32_32x32x16_bf16(pa0, PK(l0, h0), od, 0, 0, 0);
;   od = __builtin_amdgcn_mfma_f32_32x32x16_bf16(pa1, PK(l1, h1), od, 0, 0, 0);
;   od = __builtin_amdgcn_mfma_f32_32x32x16_bf16(pa2, PK(l2, h2), od, 0, 0, 0);
;   od = __builtin_amdgcn_mfma_f32_32x32x16_bf16(pa3, PK(l3, h3), od, 0, 0, 0);
;     ...
; }
; __device__ __forceinline__ void pv_d0(f32x16* o, int vb, bf16x8 pa0, bf16x8 pa1, bf16x8 pa2, bf16x8 pa3) {
;   pv_one<0>(o[0], vb, pa0, pa1, pa2, pa3); pv_one<1>(o[1], vb, pa0, pa1, pa2, pa3); pv_one<2>(o[2], vb, pa0, pa1, pa2, pa3); pv_one<3>(o[3], vb, pa0, pa1, pa2, pa3);
; template <typename TQ>
; __device__ __forceinline__ void attn_dense_body(const TQ* __restrict__ Qb, const bf16* __restrict__ Kh, const bf16* __restrict__ Vh,
;                                                 bf16* __restrict__ Ob, int seq, char* lds) {
;     ...
;   for (int j = 1; j + 1 < NT; j += 2) {
;     SBAR(); qkt(pB0, pB1, (bf16*)((char*)K_lds + cur * (int)SHM_K), qr, r32, hi);
;     finishSM(pA0, pA1, alA, l_reg, pa0, pa1, pa2, pa3); SBAR();
;     SWAIT(); SWRITE(next, SE);
;     if (j + 2 < NT) SLOAD(SO, (j + 2) * KVBLK); SBAR();
;     pv_d0(o, vb0 + prev * (int)SHM_V, pa0, pa1, pa2, pa3); partialSM_fix(pB0);
;     __syncthreads();
;     { const int t_ = prev; prev = cur; cur = next; next = t_; }
;     SBAR(); qkt(pA0, pA1, (bf16*)((char*)K_lds + cur * (int)SHM_K), qr, r32, hi);
;     finishSM(pB0, pB1, alB, l_reg, pa0, pa1, pa2, pa3); SBAR();
;     if (j + 2 < NT) { SWAIT(); SWRITE(next, SO); }
;     if (j + 3 < NT) SLOAD(SE, (j + 3) * KVBLK); SBAR();
;     pv_d0(o, vb0 + prev * (int)SHM_V, pa0, pa1, pa2, pa3); partialSM_fix(pA0);
;     __syncthreads();
	v_mfma_f32_32x32x16_bf16 v[16:31], v[96:99], v[216:219], v[16:31]
	ds_read_b64_tr_b16 v[240:241], v179 offset:25600
	ds_read_b64_tr_b16 v[242:243], v179 offset:27648
	v_exp_f32_e32 v230, v230
	v_exp_f32_e32 v231, v231
	v_add_f32_e32 v255, v225, v227
	v_mfma_f32_32x32x16_bf16 v[16:31], v[100:103], v[220:223], v[16:31]
	ds_read_b64_tr_b16 v[244:245], v179 offset:29696
	ds_read_b64_tr_b16 v[246:247], v179 offset:31744
	v_exp_f32_e32 v232, v232
	v_exp_f32_e32 v233, v233
	v_add_f32_e32 v254, v254, v228
	s_waitcnt lgkmcnt(8)
	v_mfma_f32_32x32x16_bf16 v[16:31], v[104:107], v[80:83], v[16:31]
	ds_read_b64_tr_b16 v[80:81], v179 offset:17920
	ds_read_b64_tr_b16 v[82:83], v179 offset:19968
	v_exp_f32_e32 v234, v234
	v_exp_f32_e32 v235, v235
	v_add_f32_e32 v255, v255, v229
	v_mfma_f32_32x32x16_bf16 v[16:31], v[108:111], v[84:87], v[16:31]
	ds_read_b64_tr_b16 v[84:85], v179 offset:22016
	ds_read_b64_tr_b16 v[86:87], v179 offset:24064
	v_exp_f32_e32 v236, v236
	v_exp_f32_e32 v237, v237
	v_add_f32_e32 v254, v254, v230
	s_waitcnt lgkmcnt(8)
	v_mfma_f32_32x32x16_bf16 v[32:47], v[96:99], v[88:91], v[32:47]
	ds_read_b64_tr_b16 v[88:89], v179 offset:26112
	ds_read_b64_tr_b16 v[90:91], v179 offset:28160
	v_exp_f32_e32 v238, v238
	v_exp_f32_e32 v239, v239
	v_add_f32_e32 v255, v255, v231
	v_mfma_f32_32x32x16_bf16 v[32:47], v[100:103], v[92:95], v[32:47]
	ds_read_b64_tr_b16 v[92:93], v179 offset:30208
	ds_read_b64_tr_b16 v[94:95], v179 offset:32256
	v_add_f32_e32 v254, v254, v232
	v_add_f32_e32 v255, v255, v233
	v_add_f32_e32 v254, v254, v234
	s_waitcnt lgkmcnt(8)
	v_mfma_f32_32x32x16_bf16 v[32:47], v[104:107], v[240:243], v[32:47]
	v_add_f32_e32 v255, v255, v235
	v_add_f32_e32 v254, v254, v236
	v_add_f32_e32 v255, v255, v237
	v_mfma_f32_32x32x16_bf16 v[32:47], v[108:111], v[244:247], v[32:47]
	v_add_f32_e32 v254, v254, v238
	v_add_f32_e32 v255, v255, v239
	s_waitcnt vmcnt(2)
	s_waitcnt lgkmcnt(0)
	s_barrier
	ds_read_b128 v[208:211], v144 offset:0
	ds_read_b128 v[212:215], v144 offset:8192
	ds_read_b128 v[216:219], v145 offset:0
	ds_read_b128 v[220:223], v145 offset:8192
	ds_read_b128 v[240:243], v146 offset:0
	ds_read_b128 v[244:247], v146 offset:8192
	v_mfma_f32_32x32x16_bf16 v[48:63], v[96:99], v[80:83], v[48:63]
	v_add_f32_e32 v254, v254, v255
	s_add_i32 m0, s82, 0x4000
	s_add_u32 s98, s92, 0x4000
	global_load_lds_dwordx4 v174, s[92:93]
	s_addc_u32 s99, s93, 0
	v_mfma_f32_32x32x16_bf16 v[48:63], v[100:103], v[84:87], v[48:63]
	s_add_i32 m0, s83, 0x4000
	s_nop 0
	global_load_lds_dwordx4 v175, s[92:93]
	s_mov_b64 s[92:93], s[98:99]
	v_mfma_f32_32x32x16_bf16 v[48:63], v[104:107], v[88:91], v[48:63]
	s_add_i32 m0, s80, 0x4000
	s_add_u32 s96, s90, 0x80
	s_addc_u32 s97, s91, 0
	global_load_lds_dwordx4 v249, s[90:91]
	v_mfma_f32_32x32x16_bf16 v[48:63], v[108:111], v[92:95], v[48:63]
	s_add_i32 m0, s81, 0x4000
	s_add_u32 s90, s90, 0x4000
	global_load_lds_dwordx4 v249, s[96:97]
	s_addc_u32 s91, s91, 0
	s_add_i32 s55, s55, 2
	s_cmp_ge_u32 s55, s32
	s_cbranch_scc1 .Latt_exit_0
	s_waitcnt lgkmcnt(4)
	v_mfma_f32_32x32x16_bf16 v[96:111], v[208:211], v[140:143], 0
	v_exp_f32_e32 v64, v64
	v_exp_f32_e32 v65, v65
	v_cvt_pk_bf16_f32 v224, v224, v225
	v_mfma_f32_32x32x16_bf16 v[80:95], v[212:215], v[140:143], 0
	ds_read_b128 v[208:211], v147 offset:0
	ds_read_b128 v[212:215], v147 offset:8192
	v_exp_f32_e32 v66, v66
	v_exp_f32_e32 v67, v67
	v_cvt_pk_bf16_f32 v225, v226, v227
	s_waitcnt lgkmcnt(4)
	v_mfma_f32_32x32x16_bf16 v[96:111], v[216:219], v[136:139], v[96:111]
	v_exp_f32_e32 v68, v68
	v_exp_f32_e32 v69, v69
	v_cvt_pk_bf16_f32 v226, v228, v229
	v_mfma_f32_32x32x16_bf16 v[80:95], v[220:223], v[136:139], v[80:95]
	ds_read_b128 v[216:219], v148 offset:0
	ds_read_b128 v[220:223], v148 offset:8192
	v_exp_f32_e32 v70, v70
	v_exp_f32_e32 v71, v71
	v_cvt_pk_bf16_f32 v227, v230, v231
	v_add_f32_e32 v251, v64, v66
	s_waitcnt lgkmcnt(4)
	v_mfma_f32_32x32x16_bf16 v[96:111], v[240:243], v[132:135], v[96:111]
	v_exp_f32_e32 v72, v72
	v_exp_f32_e32 v73, v73
	v_add_f32_e32 v253, v65, v67
	v_mfma_f32_32x32x16_bf16 v[80:95], v[244:247], v[132:135], v[80:95]
	ds_read_b128 v[240:243], v149 offset:0
	ds_read_b128 v[244:247], v149 offset:8192
	v_exp_f32_e32 v74, v74
	v_exp_f32_e32 v75, v75
	v_add_f32_e32 v251, v251, v68
	s_waitcnt lgkmcnt(4)
	v_mfma_f32_32x32x16_bf16 v[96:111], v[208:211], v[128:131], v[96:111]
	v_exp_f32_e32 v76, v76
	v_exp_f32_e32 v77, v77
	v_add_f32_e32 v253, v253, v69
	v_cvt_pk_bf16_f32 v228, v232, v233
	v_mfma_f32_32x32x16_bf16 v[80:95], v[212:215], v[128:131], v[80:95]
	ds_read_b128 v[208:211], v150 offset:0
	ds_read_b128 v[212:215], v150 offset:8192
	v_exp_f32_e32 v78, v78
	v_exp_f32_e32 v79, v79
	v_add_f32_e32 v251, v251, v70
	v_cvt_pk_bf16_f32 v229, v234, v235
	s_waitcnt lgkmcnt(4)
	v_mfma_f32_32x32x16_bf16 v[96:111], v[216:219], v[124:127], v[96:111]
	v_add_f32_e32 v253, v253, v71
	v_cvt_pk_bf16_f32 v230, v236, v237
	v_cvt_pk_bf16_f32 v231, v238, v239
	v_add_f32_e32 v251, v251, v72
	v_mfma_f32_32x32x16_bf16 v[80:95], v[220:223], v[124:127], v[80:95]
	ds_read_b128 v[216:219], v151 offset:0
	ds_read_b128 v[220:223], v151 offset:8192
	v_add_f32_e32 v253, v253, v73
	v_cvt_pk_bf16_f32 v232, v64, v65
	v_cvt_pk_bf16_f32 v233, v66, v67
	s_waitcnt lgkmcnt(4)
	v_mfma_f32_32x32x16_bf16 v[96:111], v[240:243], v[120:123], v[96:111]
	v_add_f32_e32 v251, v251, v74
	v_cvt_pk_bf16_f32 v234, v68, v69
	v_cvt_pk_bf16_f32 v235, v70, v71
	v_mfma_f32_32x32x16_bf16 v[80:95], v[244:247], v[120:123], v[80:95]
	ds_read_b64_tr_b16 v[240:241], v179 offset:32768
	ds_read_b64_tr_b16 v[242:243], v179 offset:34816
	ds_read_b64_tr_b16 v[244:245], v179 offset:36864
	ds_read_b64_tr_b16 v[246:247], v179 offset:38912
	v_add_f32_e32 v253, v253, v75
	v_add_f32_e32 v251, v251, v76
	v_cvt_pk_bf16_f32 v236, v72, v73
	v_cvt_pk_bf16_f32 v237, v74, v75
	s_waitcnt lgkmcnt(6)
; #define SBAR() __builtin_amdgcn_sched_barrier(0)
; __device__ __forceinline__ void partialSM_fix(f32x16& p0) { for (int r = 0; r < 16; ++r) p0[r] = __builtin_amdgcn_exp2f(p0[r]); }
; template <int D0> __device__ __forceinline__ void pv_one(f32x16& od, int vb, bf16x8 pa0, bf16x8 pa1, bf16x8 pa2, bf16x8 pa3) {
;   const s16x4 l0 = tr_read<v_rd_off(D0, 0, 0)>(vb), h0 = tr_read<v_rd_off(D0, 0, 1)>(vb), l1 = tr_read<v_rd_off(D0, 1, 0)>(vb), h1 = tr_read<v_rd_off(D0, 1, 1)>(vb);
;   const s16x4 l2 = tr_read<v_rd_off(D0, 2, 0)>(vb), h2 = tr_read<v_rd_off(D0, 2, 1)>(vb), l3 = tr_read<v_rd_off(D0, 3, 0)>(vb), h3 = tr_read<v_rd_off(D0, 3, 1)>(vb);
;   asm volatile("s_waitcnt lgkmcnt(0)" ::: "memory"); SBAR();
;     ...
;   od = __builtin_amdgcn_mfma_f32_32x32x16_bf16(pa0, PK(l0, h0), od, 0, 0, 0);
;   od = __builtin_amdgcn_mfma_f32_32x32x16_bf16(pa1, PK(l1, h1), od, 0, 0, 0);
;   od = __builtin_amdgcn_mfma_f32_32x32x16_bf16(pa2, PK(l2, h2), od, 0, 0, 0);
;   od = __builtin_amdgcn_mfma_f32_32x32x16_bf16(pa3, PK(l3, h3), od, 0, 0, 0);
;     ...
; }
; __device__ __forceinline__ void pv_d0(f32x16* o, int vb, bf16x8 pa0, bf16x8 pa1, bf16x8 pa2, bf16x8 pa3) {
;   pv_one<0>(o[0], vb, pa0, pa1, pa2, pa3); pv_one<1>(o[1], vb, pa0, pa1, pa2, pa3); pv_one<2>(o[2], vb, pa0, pa1, pa2, pa3); pv_one<3>(o[3], vb, pa0, pa1, pa2, pa3);
; template <typename TQ>
; __device__ __forceinline__ void attn_dense_body(const TQ* __restrict__ Qb, const bf16* __restrict__ Kh, const bf16* __restrict__ Vh,
;                                                 bf16* __restrict__ Ob, int seq, char* lds) {
;     ...
;   for (int j = 1; j + 1 < NT; j += 2) {
;     SBAR(); qkt(pB0, pB1, (bf16*)((char*)K_lds + cur * (int)SHM_K), qr, r32, hi);
;     finishSM(pA0, pA1, alA, l_reg, pa0, pa1, pa2, pa3); SBAR();
;     SWAIT(); SWRITE(next, SE);
;     if (j + 2 < NT) SLOAD(SO, (j + 2) * KVBLK); SBAR();
;     pv_d0(o, vb0 + prev * (int)SHM_V, pa0, pa1, pa2, pa3); partialSM_fix(pB0);
;     __syncthreads();
;     { const int t_ = prev; prev = cur; cur = next; next = t_; }
;     SBAR(); qkt(pA0, pA1, (bf16*)((char*)K_lds + cur * (int)SHM_K), qr, r32, hi);
;     finishSM(pB0, pB1, alB, l_reg, pa0, pa1, pa2, pa3); SBAR();
;     if (j + 2 < NT) { SWAIT(); SWRITE(next, SO); }
;     if (j + 3 < NT) SLOAD(SE, (j + 3) * KVBLK); SBAR();
;     pv_d0(o, vb0 + prev * (int)SHM_V, pa0, pa1, pa2, pa3); partialSM_fix(pA0);
;     __syncthreads();
	v_mfma_f32_32x32x16_bf16 v[96:111], v[208:211], v[116:119], v[96:111]
	v_add_f32_e32 v253, v253, v77
	v_add_f32_e32 v251, v251, v78
	v_mfma_f32_32x32x16_bf16 v[80:95], v[212:215], v[116:119], v[80:95]
	ds_read_b64_tr_b16 v[208:209], v179 offset:40960
	ds_read_b64_tr_b16 v[210:211], v179 offset:43008
	ds_read_b64_tr_b16 v[212:213], v179 offset:45056
	ds_read_b64_tr_b16 v[214:215], v179 offset:47104
	v_add_f32_e32 v253, v253, v79
	v_cvt_pk_bf16_f32 v238, v76, v77
	v_cvt_pk_bf16_f32 v239, v78, v79
	s_waitcnt lgkmcnt(8)
	v_mfma_f32_32x32x16_bf16 v[96:111], v[216:219], v[112:115], v[96:111]
	v_add_f32_e32 v251, v251, v253
	v_add_f32_e32 v254, v254, v251
	v_mfma_f32_32x32x16_bf16 v[80:95], v[220:223], v[112:115], v[80:95]
	ds_read_b64_tr_b16 v[216:217], v179 offset:33280
	ds_read_b64_tr_b16 v[218:219], v179 offset:35328
	ds_read_b64_tr_b16 v[220:221], v179 offset:37376
	ds_read_b64_tr_b16 v[222:223], v179 offset:39424
	v_add_f32_e32 v169, v169, v254
	s_waitcnt lgkmcnt(8)
	v_mfma_f32_32x32x16_bf16 v[0:15], v[224:227], v[240:243], v[0:15]
	ds_read_b64_tr_b16 v[64:65], v179 offset:41472
	ds_read_b64_tr_b16 v[66:67], v179 offset:43520
	v_mfma_f32_32x32x16_bf16 v[0:15], v[228:231], v[244:247], v[0:15]
	ds_read_b64_tr_b16 v[68:69], v179 offset:45568
	ds_read_b64_tr_b16 v[70:71], v179 offset:47616
	v_exp_f32_e32 v96, v96
	v_exp_f32_e32 v97, v97
	s_waitcnt lgkmcnt(8)
	v_mfma_f32_32x32x16_bf16 v[0:15], v[232:235], v[208:211], v[0:15]
	ds_read_b64_tr_b16 v[72:73], v179 offset:33792
	ds_read_b64_tr_b16 v[74:75], v179 offset:35840
	v_exp_f32_e32 v98, v98
	v_exp_f32_e32 v99, v99
	v_mfma_f32_32x32x16_bf16 v[0:15], v[236:239], v[212:215], v[0:15]
	ds_read_b64_tr_b16 v[76:77], v179 offset:37888
	ds_read_b64_tr_b16 v[78:79], v179 offset:39936
	v_exp_f32_e32 v100, v100
	v_exp_f32_e32 v101, v101
	v_add_f32_e32 v254, v96, v98
	s_waitcnt lgkmcnt(8)
	v_mfma_f32_32x32x16_bf16 v[16:31], v[224:227], v[216:219], v[16:31]
	ds_read_b64_tr_b16 v[240:241], v179 offset:41984
	ds_read_b64_tr_b16 v[242:243], v179 offset:44032
	v_exp_f32_e32 v102, v102
	v_exp_f32_e32 v103, v103
	v_add_f32_e32 v255, v97, v99
	v_mfma_f32_32x32x16_bf16 v[16:31], v[228:231], v[220:223], v[16:31]
	ds_read_b64_tr_b16 v[244:245], v179 offset:46080
	ds_read_b64_tr_b16 v[246:247], v179 offset:48128
	v_exp_f32_e32 v104, v104
	v_exp_f32_e32 v105, v105
	v_add_f32_e32 v254, v254, v100
	s_waitcnt lgkmcnt(8)
	v_mfma_f32_32x32x16_bf16 v[16:31], v[232:235], v[64:67], v[16:31]
	ds_read_b64_tr_b16 v[64:65], v179 offset:34304
	ds_read_b64_tr_b16 v[66:67], v179 offset:36352
	v_exp_f32_e32 v106, v106
	v_exp_f32_e32 v107, v107
	v_add_f32_e32 v255, v255, v101
	v_mfma_f32_32x32x16_bf16 v[16:31], v[236:239], v[68:71], v[16:31]
	ds_read_b64_tr_b16 v[68:69], v179 offset:38400
	ds_read_b64_tr_b16 v[70:71], v179 offset:40448
	v_exp_f32_e32 v108, v108
	v_exp_f32_e32 v109, v109
	v_add_f32_e32 v254, v254, v102
	s_waitcnt lgkmcnt(8)
	v_mfma_f32_32x32x16_bf16 v[32:47], v[224:227], v[72:75], v[32:47]
	ds_read_b64_tr_b16 v[72:73], v179 offset:42496
	ds_read_b64_tr_b16 v[74:75], v179 offset:44544
	v_exp_f32_e32 v110, v110
	v_exp_f32_e32 v111, v111
	v_add_f32_e32 v255, v255, v103
	v_mfma_f32_32x32x16_bf16 v[32:47], v[228:231], v[76:79], v[32:47]
	ds_read_b64_tr_b16 v[76:77], v179 offset:46592
	ds_read_b64_tr_b16 v[78:79], v179 offset:48640
	v_add_f32_e32 v254, v254, v104
	v_add_f32_e32 v255, v255, v105
	v_add_f32_e32 v254, v254, v106
	s_waitcnt lgkmcnt(8)
	v_mfma_f32_32x32x16_bf16 v[32:47], v[232:235], v[240:243], v[32:47]
	v_add_f32_e32 v255, v255, v107
	v_add_f32_e32 v254, v254, v108
	v_add_f32_e32 v255, v255, v109
	v_mfma_f32_32x32x16_bf16 v[32:47], v[236:239], v[244:247], v[32:47]
	v_add_f32_e32 v254, v254, v110
	v_add_f32_e32 v255, v255, v111
	s_waitcnt vmcnt(2)
	s_waitcnt lgkmcnt(0)
	s_barrier
	ds_read_b128 v[208:211], v144 offset:16384
	ds_read_b128 v[212:215], v144 offset:24576
	ds_read_b128 v[216:219], v145 offset:16384
	ds_read_b128 v[220:223], v145 offset:24576
	ds_read_b128 v[240:243], v146 offset:16384
	ds_read_b128 v[244:247], v146 offset:24576
	v_mfma_f32_32x32x16_bf16 v[48:63], v[224:227], v[64:67], v[48:63]
	v_add_f32_e32 v254, v254, v255
	s_add_i32 m0, s82, 0x8000
	s_add_u32 s98, s92, 0x4000
	global_load_lds_dwordx4 v174, s[92:93]
	s_addc_u32 s99, s93, 0
	v_mfma_f32_32x32x16_bf16 v[48:63], v[228:231], v[68:71], v[48:63]
	s_add_i32 m0, s83, 0x8000
	s_nop 0
	global_load_lds_dwordx4 v175, s[92:93]
	s_mov_b64 s[92:93], s[98:99]
	v_mfma_f32_32x32x16_bf16 v[48:63], v[232:235], v[72:75], v[48:63]
	s_add_i32 m0, s80, 0x8000
	s_add_u32 s96, s90, 0x80
	s_addc_u32 s97, s91, 0
	global_load_lds_dwordx4 v249, s[90:91]
	v_mfma_f32_32x32x16_bf16 v[48:63], v[236:239], v[76:79], v[48:63]
	s_add_i32 m0, s81, 0x8000
	s_add_u32 s90, s90, 0x4000
	global_load_lds_dwordx4 v249, s[96:97]
	s_addc_u32 s91, s91, 0
	s_waitcnt lgkmcnt(4)
	v_mfma_f32_32x32x16_bf16 v[224:239], v[208:211], v[140:143], 0
	v_exp_f32_e32 v80, v80
	v_exp_f32_e32 v81, v81
	v_cvt_pk_bf16_f32 v96, v96, v97
	v_mfma_f32_32x32x16_bf16 v[64:79], v[212:215], v[140:143], 0
	ds_read_b128 v[208:211], v147 offset:16384
	ds_read_b128 v[212:215], v147 offset:24576
	v_exp_f32_e32 v82, v82
	v_exp_f32_e32 v83, v83
	v_cvt_pk_bf16_f32 v97, v98, v99
	s_waitcnt lgkmcnt(4)
	v_mfma_f32_32x32x16_bf16 v[224:239], v[216:219], v[136:139], v[224:239]
	v_exp_f32_e32 v84, v84
	v_exp_f32_e32 v85, v85
	v_cvt_pk_bf16_f32 v98, v100, v101
	v_mfma_f32_32x32x16_bf16 v[64:79], v[220:223], v[136:139], v[64:79]
	ds_read_b128 v[216:219], v148 offset:16384
	ds_read_b128 v[220:223], v148 offset:24576
	v_exp_f32_e32 v86, v86
	v_exp_f32_e32 v87, v87
	v_cvt_pk_bf16_f32 v99, v102, v103
	v_add_f32_e32 v251, v80, v82
	s_waitcnt lgkmcnt(4)
; #define SBAR() __builtin_amdgcn_sched_barrier(0)
; __device__ __forceinline__ void qkt(f32x16& p0, f32x16& p1, const bf16* Ks, const bf16x8* qr, int r32, int hi) {
;   p0 = f32x16{}; p1 = f32x16{};
;   for (int d0 = 0; d0 < 8; ++d0) { int cb = (d0 * 16 + hi * 8) * 2;
;     bf16x8 b0 = *reinterpret_cast<const bf16x8*>((const char*)Ks + KSWZ(r32, cb));
;     bf16x8 b1 = *reinterpret_cast<const bf16x8*>((const char*)Ks + KSWZ(32 + r32, cb));
;     p0 = __builtin_amdgcn_mfma_f32_32x32x16_bf16(b0, qr[d0], p0, 0, 0, 0);
;     p1 = __builtin_amdgcn_mfma_f32_32x32x16_bf16(b1, qr[d0], p1, 0, 0, 0); }
; }
; template <int D0> __device__ __forceinline__ void pv_one(f32x16& od, int vb, bf16x8 pa0, bf16x8 pa1, bf16x8 pa2, bf16x8 pa3) {
;   const s16x4 l0 = tr_read<v_rd_off(D0, 0, 0)>(vb), h0 = tr_read<v_rd_off(D0, 0, 1)>(vb), l1 = tr_read<v_rd_off(D0, 1, 0)>(vb), h1 = tr_read<v_rd_off(D0, 1, 1)>(vb);
;   const s16x4 l2 = tr_read<v_rd_off(D0, 2, 0)>(vb), h2 = tr_read<v_rd_off(D0, 2, 1)>(vb), l3 = tr_read<v_rd_off(D0, 3, 0)>(vb), h3 = tr_read<v_rd_off(D0, 3, 1)>(vb);
;   asm volatile("s_waitcnt lgkmcnt(0)" ::: "memory"); SBAR();
;     ...
;   od = __builtin_amdgcn_mfma_f32_32x32x16_bf16(pa0, PK(l0, h0), od, 0, 0, 0);
;   od = __builtin_amdgcn_mfma_f32_32x32x16_bf16(pa1, PK(l1, h1), od, 0, 0, 0);
;   od = __builtin_amdgcn_mfma_f32_32x32x16_bf16(pa2, PK(l2, h2), od, 0, 0, 0);
;   od = __builtin_amdgcn_mfma_f32_32x32x16_bf16(pa3, PK(l3, h3), od, 0, 0, 0);
;     ...
; }
; __device__ __forceinline__ void pv_d0(f32x16* o, int vb, bf16x8 pa0, bf16x8 pa1, bf16x8 pa2, bf16x8 pa3) {
;   pv_one<0>(o[0], vb, pa0, pa1, pa2, pa3); pv_one<1>(o[1], vb, pa0, pa1, pa2, pa3); pv_one<2>(o[2], vb, pa0, pa1, pa2, pa3); pv_one<3>(o[3], vb, pa0, pa1, pa2, pa3);
	v_mfma_f32_32x32x16_bf16 v[224:239], v[240:243], v[132:135], v[224:239]
	v_exp_f32_e32 v88, v88
	v_exp_f32_e32 v89, v89
	v_add_f32_e32 v253, v81, v83
	v_mfma_f32_32x32x16_bf16 v[64:79], v[244:247], v[132:135], v[64:79]
	ds_read_b128 v[240:243], v149 offset:16384
	ds_read_b128 v[244:247], v149 offset:24576
	v_exp_f32_e32 v90, v90
	v_exp_f32_e32 v91, v91
	v_add_f32_e32 v251, v251, v84
	s_waitcnt lgkmcnt(4)
	v_mfma_f32_32x32x16_bf16 v[224:239], v[208:211], v[128:131], v[224:239]
	v_exp_f32_e32 v92, v92
	v_exp_f32_e32 v93, v93
	v_add_f32_e32 v253, v253, v85
	v_cvt_pk_bf16_f32 v100, v104, v105
	v_mfma_f32_32x32x16_bf16 v[64:79], v[212:215], v[128:131], v[64:79]
	ds_read_b128 v[208:211], v150 offset:16384
	ds_read_b128 v[212:215], v150 offset:24576
	v_exp_f32_e32 v94, v94
	v_exp_f32_e32 v95, v95
	v_add_f32_e32 v251, v251, v86
	v_cvt_pk_bf16_f32 v101, v106, v107
	s_waitcnt lgkmcnt(4)
	v_mfma_f32_32x32x16_bf16 v[224:239], v[216:219], v[124:127], v[224:239]
	v_add_f32_e32 v253, v253, v87
	v_cvt_pk_bf16_f32 v102, v108, v109
	v_cvt_pk_bf16_f32 v103, v110, v111
	v_add_f32_e32 v251, v251, v88
	v_mfma_f32_32x32x16_bf16 v[64:79], v[220:223], v[124:127], v[64:79]
	ds_read_b128 v[216:219], v151 offset:16384
	ds_read_b128 v[220:223], v151 offset:24576
	v_add_f32_e32 v253, v253, v89
	v_cvt_pk_bf16_f32 v104, v80, v81
	v_cvt_pk_bf16_f32 v105, v82, v83
	s_waitcnt lgkmcnt(4)
	v_mfma_f32_32x32x16_bf16 v[224:239], v[240:243], v[120:123], v[224:239]
	v_add_f32_e32 v251, v251, v90
	v_cvt_pk_bf16_f32 v106, v84, v85
	v_cvt_pk_bf16_f32 v107, v86, v87
	v_mfma_f32_32x32x16_bf16 v[64:79], v[244:247], v[120:123], v[64:79]
	ds_read_b64_tr_b16 v[240:241], v179 offset:0
	ds_read_b64_tr_b16 v[242:243], v179 offset:2048
	ds_read_b64_tr_b16 v[244:245], v179 offset:4096
	ds_read_b64_tr_b16 v[246:247], v179 offset:6144
	v_add_f32_e32 v253, v253, v91
	v_add_f32_e32 v251, v251, v92
	v_cvt_pk_bf16_f32 v108, v88, v89
	v_cvt_pk_bf16_f32 v109, v90, v91
	s_waitcnt lgkmcnt(6)
	v_mfma_f32_32x32x16_bf16 v[224:239], v[208:211], v[116:119], v[224:239]
	v_add_f32_e32 v253, v253, v93
	v_add_f32_e32 v251, v251, v94
	v_mfma_f32_32x32x16_bf16 v[64:79], v[212:215], v[116:119], v[64:79]
	ds_read_b64_tr_b16 v[208:209], v179 offset:8192
	ds_read_b64_tr_b16 v[210:211], v179 offset:10240
	ds_read_b64_tr_b16 v[212:213], v179 offset:12288
	ds_read_b64_tr_b16 v[214:215], v179 offset:14336
	v_add_f32_e32 v253, v253, v95
	v_cvt_pk_bf16_f32 v110, v92, v93
	v_cvt_pk_bf16_f32 v111, v94, v95
	s_waitcnt lgkmcnt(8)
	v_mfma_f32_32x32x16_bf16 v[224:239], v[216:219], v[112:115], v[224:239]
	v_add_f32_e32 v251, v251, v253
	v_add_f32_e32 v254, v254, v251
	v_mfma_f32_32x32x16_bf16 v[64:79], v[220:223], v[112:115], v[64:79]
	ds_read_b64_tr_b16 v[216:217], v179 offset:512
	ds_read_b64_tr_b16 v[218:219], v179 offset:2560
	ds_read_b64_tr_b16 v[220:221], v179 offset:4608
	ds_read_b64_tr_b16 v[222:223], v179 offset:6656
	v_add_f32_e32 v169, v169, v254
	s_waitcnt lgkmcnt(8)
	v_mfma_f32_32x32x16_bf16 v[0:15], v[96:99], v[240:243], v[0:15]
	ds_read_b64_tr_b16 v[80:81], v179 offset:8704
	ds_read_b64_tr_b16 v[82:83], v179 offset:10752
	v_mfma_f32_32x32x16_bf16 v[0:15], v[100:103], v[244:247], v[0:15]
	ds_read_b64_tr_b16 v[84:85], v179 offset:12800
	ds_read_b64_tr_b16 v[86:87], v179 offset:14848
	v_exp_f32_e32 v224, v224
	v_exp_f32_e32 v225, v225
	s_waitcnt lgkmcnt(8)
	v_mfma_f32_32x32x16_bf16 v[0:15], v[104:107], v[208:211], v[0:15]
	ds_read_b64_tr_b16 v[88:89], v179 offset:1024
	ds_read_b64_tr_b16 v[90:91], v179 offset:3072
	v_exp_f32_e32 v226, v226
	v_exp_f32_e32 v227, v227
	v_mfma_f32_32x32x16_bf16 v[0:15], v[108:111], v[212:215], v[0:15]
	ds_read_b64_tr_b16 v[92:93], v179 offset:5120
	ds_read_b64_tr_b16 v[94:95], v179 offset:7168
	v_exp_f32_e32 v228, v228
	v_exp_f32_e32 v229, v229
	v_add_f32_e32 v254, v224, v226
	s_waitcnt lgkmcnt(8)
	v_mfma_f32_32x32x16_bf16 v[16:31], v[96:99], v[216:219], v[16:31]
	ds_read_b64_tr_b16 v[240:241], v179 offset:9216
	ds_read_b64_tr_b16 v[242:243], v179 offset:11264
	v_exp_f32_e32 v230, v230
	v_exp_f32_e32 v231, v231
	v_add_f32_e32 v255, v225, v227
	v_mfma_f32_32x32x16_bf16 v[16:31], v[100:103], v[220:223], v[16:31]
	ds_read_b64_tr_b16 v[244:245], v179 offset:13312
	ds_read_b64_tr_b16 v[246:247], v179 offset:15360
	v_exp_f32_e32 v232, v232
	v_exp_f32_e32 v233, v233
	v_add_f32_e32 v254, v254, v228
	s_waitcnt lgkmcnt(8)
	v_mfma_f32_32x32x16_bf16 v[16:31], v[104:107], v[80:83], v[16:31]
	ds_read_b64_tr_b16 v[80:81], v179 offset:1536
	ds_read_b64_tr_b16 v[82:83], v179 offset:3584
	v_exp_f32_e32 v234, v234
	v_exp_f32_e32 v235, v235
	v_add_f32_e32 v255, v255, v229
	v_mfma_f32_32x32x16_bf16 v[16:31], v[108:111], v[84:87], v[16:31]
	ds_read_b64_tr_b16 v[84:85], v179 offset:5632
	ds_read_b64_tr_b16 v[86:87], v179 offset:7680
	v_exp_f32_e32 v236, v236
	v_exp_f32_e32 v237, v237
	v_add_f32_e32 v254, v254, v230
	s_waitcnt lgkmcnt(8)
	v_mfma_f32_32x32x16_bf16 v[32:47], v[96:99], v[88:91], v[32:47]
	ds_read_b64_tr_b16 v[88:89], v179 offset:9728
	ds_read_b64_tr_b16 v[90:91], v179 offset:11776
	v_exp_f32_e32 v238, v238
	v_exp_f32_e32 v239, v239
	v_add_f32_e32 v255, v255, v231
	v_mfma_f32_32x32x16_bf16 v[32:47], v[100:103], v[92:95], v[32:47]
	ds_read_b64_tr_b16 v[92:93], v179 offset:13824
	ds_read_b64_tr_b16 v[94:95], v179 offset:15872
	v_add_f32_e32 v254, v254, v232
	v_add_f32_e32 v255, v255, v233
	v_add_f32_e32 v254, v254, v234
	s_waitcnt lgkmcnt(8)
	v_mfma_f32_32x32x16_bf16 v[32:47], v[104:107], v[240:243], v[32:47]
	v_add_f32_e32 v255, v255, v235
	v_add_f32_e32 v254, v254, v236
	v_add_f32_e32 v255, v255, v237
	v_mfma_f32_32x32x16_bf16 v[32:47], v[108:111], v[244:247], v[32:47]
	v_add_f32_e32 v254, v254, v238
	v_add_f32_e32 v255, v255, v239
	s_waitcnt vmcnt(2)
	s_waitcnt lgkmcnt(0)
	s_barrier
; #define SBAR() __builtin_amdgcn_sched_barrier(0)
; __device__ __forceinline__ void partialSM_fix(f32x16& p0) { for (int r = 0; r < 16; ++r) p0[r] = __builtin_amdgcn_exp2f(p0[r]); }
; #define SLOAD(i, k0) do { sr_[i].vs0 = St::ld8(&Vh[(long)((k0) + sr) * LDK + sc]); sr_[i].vs1 = St::ld8(&Vh[(long)((k0) + 32 + sr) * LDK + sc]); \
;     sr_[i].ks0 = St::ld8(&Kh[(long)((k0) + sr) * LDK + sc]); sr_[i].ks1 = St::ld8(&Kh[(long)((k0) + 32 + sr) * LDK + sc]); } while (0)
; #define SWAIT() do { if constexpr (SDEPTH == 2) asm volatile("s_waitcnt vmcnt(4)" ::: "memory"); else asm volatile("s_waitcnt vmcnt(0)" ::: "memory"); } while (0)
; __device__ __forceinline__ void qkt(f32x16& p0, f32x16& p1, const bf16* Ks, const bf16x8* qr, int r32, int hi) {
;   p0 = f32x16{}; p1 = f32x16{};
;   for (int d0 = 0; d0 < 8; ++d0) { int cb = (d0 * 16 + hi * 8) * 2;
;     bf16x8 b0 = *reinterpret_cast<const bf16x8*>((const char*)Ks + KSWZ(r32, cb));
;     bf16x8 b1 = *reinterpret_cast<const bf16x8*>((const char*)Ks + KSWZ(32 + r32, cb));
;     p0 = __builtin_amdgcn_mfma_f32_32x32x16_bf16(b0, qr[d0], p0, 0, 0, 0);
;     p1 = __builtin_amdgcn_mfma_f32_32x32x16_bf16(b1, qr[d0], p1, 0, 0, 0); }
; }
; template <typename TQ>
; __device__ __forceinline__ void attn_dense_body(const TQ* __restrict__ Qb, const bf16* __restrict__ Kh, const bf16* __restrict__ Vh,
;                                                 bf16* __restrict__ Ob, int seq, char* lds) {
;     ...
;     SBAR(); qkt(pB0, pB1, (bf16*)((char*)K_lds + cur * (int)SHM_K), qr, r32, hi);
;     finishSM(pA0, pA1, alA, l_reg, pa0, pa1, pa2, pa3); SBAR();
;     SWAIT(); SWRITE(next, SE);
;     if (j + 2 < NT) SLOAD(SO, (j + 2) * KVBLK); SBAR();
;     pv_d0(o, vb0 + prev * (int)SHM_V, pa0, pa1, pa2, pa3); partialSM_fix(pB0);
;     __syncthreads();
;     { const int t_ = prev; prev = cur; cur = next; next = t_; }
;     SBAR(); qkt(pA0, pA1, (bf16*)((char*)K_lds + cur * (int)SHM_K), qr, r32, hi);
;     finishSM(pB0, pB1, alB, l_reg, pa0, pa1, pa2, pa3); SBAR();
;     if (j + 2 < NT) { SWAIT(); SWRITE(next, SO); }
;     if (j + 3 < NT) SLOAD(SE, (j + 3) * KVBLK); SBAR();
;     pv_d0(o, vb0 + prev * (int)SHM_V, pa0, pa1, pa2, pa3); partialSM_fix(pA0);
;     __syncthreads();
	ds_read_b128 v[208:211], v144 offset:32768
	ds_read_b128 v[212:215], v144 offset:40960
	ds_read_b128 v[216:219], v145 offset:32768
	ds_read_b128 v[220:223], v145 offset:40960
	ds_read_b128 v[240:243], v146 offset:32768
	ds_read_b128 v[244:247], v146 offset:40960
	v_mfma_f32_32x32x16_bf16 v[48:63], v[96:99], v[80:83], v[48:63]
	v_add_f32_e32 v254, v254, v255
	s_add_i32 m0, s82, 0x0
	s_add_u32 s98, s92, 0x4000
	global_load_lds_dwordx4 v174, s[92:93]
	s_addc_u32 s99, s93, 0
	v_mfma_f32_32x32x16_bf16 v[48:63], v[100:103], v[84:87], v[48:63]
	s_add_i32 m0, s83, 0x0
	s_nop 0
	global_load_lds_dwordx4 v175, s[92:93]
	s_mov_b64 s[92:93], s[98:99]
	v_mfma_f32_32x32x16_bf16 v[48:63], v[104:107], v[88:91], v[48:63]
	s_add_i32 m0, s80, 0x0
	s_add_u32 s96, s90, 0x80
	s_addc_u32 s97, s91, 0
	global_load_lds_dwordx4 v249, s[90:91]
	v_mfma_f32_32x32x16_bf16 v[48:63], v[108:111], v[92:95], v[48:63]
	s_add_i32 m0, s81, 0x0
	s_add_u32 s90, s90, 0x4000
	global_load_lds_dwordx4 v249, s[96:97]
	s_addc_u32 s91, s91, 0
	s_add_i32 s55, s55, 2
	s_cmp_ge_u32 s55, s32
	s_cbranch_scc1 .Latt_exit_1
	s_waitcnt lgkmcnt(4)
	v_mfma_f32_32x32x16_bf16 v[96:111], v[208:211], v[140:143], 0
	v_exp_f32_e32 v64, v64
	v_exp_f32_e32 v65, v65
	v_cvt_pk_bf16_f32 v224, v224, v225
	v_mfma_f32_32x32x16_bf16 v[80:95], v[212:215], v[140:143], 0
	ds_read_b128 v[208:211], v147 offset:32768
	ds_read_b128 v[212:215], v147 offset:40960
	v_exp_f32_e32 v66, v66
	v_exp_f32_e32 v67, v67
	v_cvt_pk_bf16_f32 v225, v226, v227
	s_waitcnt lgkmcnt(4)
	v_mfma_f32_32x32x16_bf16 v[96:111], v[216:219], v[136:139], v[96:111]
	v_exp_f32_e32 v68, v68
	v_exp_f32_e32 v69, v69
	v_cvt_pk_bf16_f32 v226, v228, v229
	v_mfma_f32_32x32x16_bf16 v[80:95], v[220:223], v[136:139], v[80:95]
	ds_read_b128 v[216:219], v148 offset:32768
	ds_read_b128 v[220:223], v148 offset:40960
	v_exp_f32_e32 v70, v70
	v_exp_f32_e32 v71, v71
	v_cvt_pk_bf16_f32 v227, v230, v231
	v_add_f32_e32 v251, v64, v66
	s_waitcnt lgkmcnt(4)
	v_mfma_f32_32x32x16_bf16 v[96:111], v[240:243], v[132:135], v[96:111]
	v_exp_f32_e32 v72, v72
	v_exp_f32_e32 v73, v73
	v_add_f32_e32 v253, v65, v67
	v_mfma_f32_32x32x16_bf16 v[80:95], v[244:247], v[132:135], v[80:95]
	ds_read_b128 v[240:243], v149 offset:32768
	ds_read_b128 v[244:247], v149 offset:40960
	v_exp_f32_e32 v74, v74
	v_exp_f32_e32 v75, v75
	v_add_f32_e32 v251, v251, v68
	s_waitcnt lgkmcnt(4)
	v_mfma_f32_32x32x16_bf16 v[96:111], v[208:211], v[128:131], v[96:111]
	v_exp_f32_e32 v76, v76
	v_exp_f32_e32 v77, v77
	v_add_f32_e32 v253, v253, v69
	v_cvt_pk_bf16_f32 v228, v232, v233
	v_mfma_f32_32x32x16_bf16 v[80:95], v[212:215], v[128:131], v[80:95]
	ds_read_b128 v[208:211], v150 offset:32768
	ds_read_b128 v[212:215], v150 offset:40960
	v_exp_f32_e32 v78, v78
	v_exp_f32_e32 v79, v79
	v_add_f32_e32 v251, v251, v70
	v_cvt_pk_bf16_f32 v229, v234, v235
	s_waitcnt lgkmcnt(4)
	v_mfma_f32_32x32x16_bf16 v[96:111], v[216:219], v[124:127], v[96:111]
	v_add_f32_e32 v253, v253, v71
	v_cvt_pk_bf16_f32 v230, v236, v237
	v_cvt_pk_bf16_f32 v231, v238, v239
	v_add_f32_e32 v251, v251, v72
	v_mfma_f32_32x32x16_bf16 v[80:95], v[220:223], v[124:127], v[80:95]
	ds_read_b128 v[216:219], v151 offset:32768
	ds_read_b128 v[220:223], v151 offset:40960
	v_add_f32_e32 v253, v253, v73
	v_cvt_pk_bf16_f32 v232, v64, v65
	v_cvt_pk_bf16_f32 v233, v66, v67
	s_waitcnt lgkmcnt(4)
	v_mfma_f32_32x32x16_bf16 v[96:111], v[240:243], v[120:123], v[96:111]
	v_add_f32_e32 v251, v251, v74
	v_cvt_pk_bf16_f32 v234, v68, v69
	v_cvt_pk_bf16_f32 v235, v70, v71
	v_mfma_f32_32x32x16_bf16 v[80:95], v[244:247], v[120:123], v[80:95]
	ds_read_b64_tr_b16 v[240:241], v179 offset:16384
	ds_read_b64_tr_b16 v[242:243], v179 offset:18432
	ds_read_b64_tr_b16 v[244:245], v179 offset:20480
	ds_read_b64_tr_b16 v[246:247], v179 offset:22528
	v_add_f32_e32 v253, v253, v75
	v_add_f32_e32 v251, v251, v76
	v_cvt_pk_bf16_f32 v236, v72, v73
	v_cvt_pk_bf16_f32 v237, v74, v75
	s_waitcnt lgkmcnt(6)
	v_mfma_f32_32x32x16_bf16 v[96:111], v[208:211], v[116:119], v[96:111]
	v_add_f32_e32 v253, v253, v77
	v_add_f32_e32 v251, v251, v78
	v_mfma_f32_32x32x16_bf16 v[80:95], v[212:215], v[116:119], v[80:95]
	ds_read_b64_tr_b16 v[208:209], v179 offset:24576
	ds_read_b64_tr_b16 v[210:211], v179 offset:26624
	ds_read_b64_tr_b16 v[212:213], v179 offset:28672
	ds_read_b64_tr_b16 v[214:215], v179 offset:30720
	v_add_f32_e32 v253, v253, v79
	v_cvt_pk_bf16_f32 v238, v76, v77
	v_cvt_pk_bf16_f32 v239, v78, v79
	s_waitcnt lgkmcnt(8)
	v_mfma_f32_32x32x16_bf16 v[96:111], v[216:219], v[112:115], v[96:111]
	v_add_f32_e32 v251, v251, v253
	v_add_f32_e32 v254, v254, v251
	v_mfma_f32_32x32x16_bf16 v[80:95], v[220:223], v[112:115], v[80:95]
	ds_read_b64_tr_b16 v[216:217], v179 offset:16896
	ds_read_b64_tr_b16 v[218:219], v179 offset:18944
	ds_read_b64_tr_b16 v[220:221], v179 offset:20992
	ds_read_b64_tr_b16 v[222:223], v179 offset:23040
	v_add_f32_e32 v169, v169, v254
	s_waitcnt lgkmcnt(8)
	v_mfma_f32_32x32x16_bf16 v[0:15], v[224:227], v[240:243], v[0:15]
	ds_read_b64_tr_b16 v[64:65], v179 offset:25088
	ds_read_b64_tr_b16 v[66:67], v179 offset:27136
	v_mfma_f32_32x32x16_bf16 v[0:15], v[228:231], v[244:247], v[0:15]
	ds_read_b64_tr_b16 v[68:69], v179 offset:29184
	ds_read_b64_tr_b16 v[70:71], v179 offset:31232
	v_exp_f32_e32 v96, v96
	v_exp_f32_e32 v97, v97
	s_waitcnt lgkmcnt(8)
	v_mfma_f32_32x32x16_bf16 v[0:15], v[232:235], v[208:211], v[0:15]
	ds_read_b64_tr_b16 v[72:73], v179 offset:17408
	ds_read_b64_tr_b16 v[74:75], v179 offset:19456
	v_exp_f32_e32 v98, v98
	v_exp_f32_e32 v99, v99
	v_mfma_f32_32x32x16_bf16 v[0:15], v[236:239], v[212:215], v[0:15]
	ds_read_b64_tr_b16 v[76:77], v179 offset:21504
	ds_read_b64_tr_b16 v[78:79], v179 offset:23552
	v_exp_f32_e32 v100, v100
	v_exp_f32_e32 v101, v101
	v_add_f32_e32 v254, v96, v98
	s_waitcnt lgkmcnt(8)
; #define SBAR() __builtin_amdgcn_sched_barrier(0)
; __device__ __forceinline__ void partialSM_fix(f32x16& p0) { for (int r = 0; r < 16; ++r) p0[r] = __builtin_amdgcn_exp2f(p0[r]); }
; #define SLOAD(i, k0) do { sr_[i].vs0 = St::ld8(&Vh[(long)((k0) + sr) * LDK + sc]); sr_[i].vs1 = St::ld8(&Vh[(long)((k0) + 32 + sr) * LDK + sc]); \
;     sr_[i].ks0 = St::ld8(&Kh[(long)((k0) + sr) * LDK + sc]); sr_[i].ks1 = St::ld8(&Kh[(long)((k0) + 32 + sr) * LDK + sc]); } while (0)
; #define SWAIT() do { if constexpr (SDEPTH == 2) asm volatile("s_waitcnt vmcnt(4)" ::: "memory"); else asm volatile("s_waitcnt vmcnt(0)" ::: "memory"); } while (0)
; template <int D0> __device__ __forceinline__ void pv_one(f32x16& od, int vb, bf16x8 pa0, bf16x8 pa1, bf16x8 pa2, bf16x8 pa3) {
;   const s16x4 l0 = tr_read<v_rd_off(D0, 0, 0)>(vb), h0 = tr_read<v_rd_off(D0, 0, 1)>(vb), l1 = tr_read<v_rd_off(D0, 1, 0)>(vb), h1 = tr_read<v_rd_off(D0, 1, 1)>(vb);
;   const s16x4 l2 = tr_read<v_rd_off(D0, 2, 0)>(vb), h2 = tr_read<v_rd_off(D0, 2, 1)>(vb), l3 = tr_read<v_rd_off(D0, 3, 0)>(vb), h3 = tr_read<v_rd_off(D0, 3, 1)>(vb);
;   asm volatile("s_waitcnt lgkmcnt(0)" ::: "memory"); SBAR();
;     ...
;   od = __builtin_amdgcn_mfma_f32_32x32x16_bf16(pa0, PK(l0, h0), od, 0, 0, 0);
;   od = __builtin_amdgcn_mfma_f32_32x32x16_bf16(pa1, PK(l1, h1), od, 0, 0, 0);
;   od = __builtin_amdgcn_mfma_f32_32x32x16_bf16(pa2, PK(l2, h2), od, 0, 0, 0);
;   od = __builtin_amdgcn_mfma_f32_32x32x16_bf16(pa3, PK(l3, h3), od, 0, 0, 0);
;     ...
; }
; __device__ __forceinline__ void pv_d0(f32x16* o, int vb, bf16x8 pa0, bf16x8 pa1, bf16x8 pa2, bf16x8 pa3) {
;   pv_one<0>(o[0], vb, pa0, pa1, pa2, pa3); pv_one<1>(o[1], vb, pa0, pa1, pa2, pa3); pv_one<2>(o[2], vb, pa0, pa1, pa2, pa3); pv_one<3>(o[3], vb, pa0, pa1, pa2, pa3);
; template <typename TQ>
; __device__ __forceinline__ void attn_dense_body(const TQ* __restrict__ Qb, const bf16* __restrict__ Kh, const bf16* __restrict__ Vh,
;                                                 bf16* __restrict__ Ob, int seq, char* lds) {
;     ...
;     SBAR(); qkt(pB0, pB1, (bf16*)((char*)K_lds + cur * (int)SHM_K), qr, r32, hi);
;     finishSM(pA0, pA1, alA, l_reg, pa0, pa1, pa2, pa3); SBAR();
;     SWAIT(); SWRITE(next, SE);
;     if (j + 2 < NT) SLOAD(SO, (j + 2) * KVBLK); SBAR();
;     pv_d0(o, vb0 + prev * (int)SHM_V, pa0, pa1, pa2, pa3); partialSM_fix(pB0);
	v_mfma_f32_32x32x16_bf16 v[16:31], v[224:227], v[216:219], v[16:31]
	ds_read_b64_tr_b16 v[240:241], v179 offset:25600
	ds_read_b64_tr_b16 v[242:243], v179 offset:27648
	v_exp_f32_e32 v102, v102
	v_exp_f32_e32 v103, v103
	v_add_f32_e32 v255, v97, v99
	v_mfma_f32_32x32x16_bf16 v[16:31], v[228:231], v[220:223], v[16:31]
	ds_read_b64_tr_b16 v[244:245], v179 offset:29696
	ds_read_b64_tr_b16 v[246:247], v179 offset:31744
	v_exp_f32_e32 v104, v104
	v_exp_f32_e32 v105, v105
	v_add_f32_e32 v254, v254, v100
	s_waitcnt lgkmcnt(8)
	v_mfma_f32_32x32x16_bf16 v[16:31], v[232:235], v[64:67], v[16:31]
	ds_read_b64_tr_b16 v[64:65], v179 offset:17920
	ds_read_b64_tr_b16 v[66:67], v179 offset:19968
	v_exp_f32_e32 v106, v106
	v_exp_f32_e32 v107, v107
	v_add_f32_e32 v255, v255, v101
	v_mfma_f32_32x32x16_bf16 v[16:31], v[236:239], v[68:71], v[16:31]
	ds_read_b64_tr_b16 v[68:69], v179 offset:22016
	ds_read_b64_tr_b16 v[70:71], v179 offset:24064
	v_exp_f32_e32 v108, v108
	v_exp_f32_e32 v109, v109
	v_add_f32_e32 v254, v254, v102
	s_waitcnt lgkmcnt(8)
	v_mfma_f32_32x32x16_bf16 v[32:47], v[224:227], v[72:75], v[32:47]
	ds_read_b64_tr_b16 v[72:73], v179 offset:26112
	ds_read_b64_tr_b16 v[74:75], v179 offset:28160
	v_exp_f32_e32 v110, v110
	v_exp_f32_e32 v111, v111
	v_add_f32_e32 v255, v255, v103
	v_mfma_f32_32x32x16_bf16 v[32:47], v[228:231], v[76:79], v[32:47]
	ds_read_b64_tr_b16 v[76:77], v179 offset:30208
	ds_read_b64_tr_b16 v[78:79], v179 offset:32256
	v_add_f32_e32 v254, v254, v104
	v_add_f32_e32 v255, v255, v105
	v_add_f32_e32 v254, v254, v106
	s_waitcnt lgkmcnt(8)
	v_mfma_f32_32x32x16_bf16 v[32:47], v[232:235], v[240:243], v[32:47]
	v_add_f32_e32 v255, v255, v107
	v_add_f32_e32 v254, v254, v108
	v_add_f32_e32 v255, v255, v109
	v_mfma_f32_32x32x16_bf16 v[32:47], v[236:239], v[244:247], v[32:47]
	v_add_f32_e32 v254, v254, v110
	v_add_f32_e32 v255, v255, v111
	s_waitcnt vmcnt(2)
	s_waitcnt lgkmcnt(0)
	s_barrier
	ds_read_b128 v[208:211], v144 offset:0
	ds_read_b128 v[212:215], v144 offset:8192
	ds_read_b128 v[216:219], v145 offset:0
	ds_read_b128 v[220:223], v145 offset:8192
	ds_read_b128 v[240:243], v146 offset:0
	ds_read_b128 v[244:247], v146 offset:8192
	v_mfma_f32_32x32x16_bf16 v[48:63], v[224:227], v[64:67], v[48:63]
	v_add_f32_e32 v254, v254, v255
	s_add_i32 m0, s82, 0x4000
	s_add_u32 s98, s92, 0x4000
	global_load_lds_dwordx4 v174, s[92:93]
	s_addc_u32 s99, s93, 0
	v_mfma_f32_32x32x16_bf16 v[48:63], v[228:231], v[68:71], v[48:63]
	s_add_i32 m0, s83, 0x4000
	s_nop 0
	global_load_lds_dwordx4 v175, s[92:93]
	s_mov_b64 s[92:93], s[98:99]
	v_mfma_f32_32x32x16_bf16 v[48:63], v[232:235], v[72:75], v[48:63]
	s_add_i32 m0, s80, 0x4000
	s_add_u32 s96, s90, 0x80
	s_addc_u32 s97, s91, 0
	global_load_lds_dwordx4 v249, s[90:91]
	v_mfma_f32_32x32x16_bf16 v[48:63], v[236:239], v[76:79], v[48:63]
	s_add_i32 m0, s81, 0x4000
	s_add_u32 s90, s90, 0x4000
	global_load_lds_dwordx4 v249, s[96:97]
	s_addc_u32 s91, s91, 0
	s_waitcnt lgkmcnt(4)
	v_mfma_f32_32x32x16_bf16 v[224:239], v[208:211], v[140:143], 0
	v_exp_f32_e32 v80, v80
	v_exp_f32_e32 v81, v81
	v_cvt_pk_bf16_f32 v96, v96, v97
	v_mfma_f32_32x32x16_bf16 v[64:79], v[212:215], v[140:143], 0
	ds_read_b128 v[208:211], v147 offset:0
	ds_read_b128 v[212:215], v147 offset:8192
	v_exp_f32_e32 v82, v82
	v_exp_f32_e32 v83, v83
	v_cvt_pk_bf16_f32 v97, v98, v99
	s_waitcnt lgkmcnt(4)
	v_mfma_f32_32x32x16_bf16 v[224:239], v[216:219], v[136:139], v[224:239]
	v_exp_f32_e32 v84, v84
	v_exp_f32_e32 v85, v85
	v_cvt_pk_bf16_f32 v98, v100, v101
	v_mfma_f32_32x32x16_bf16 v[64:79], v[220:223], v[136:139], v[64:79]
	ds_read_b128 v[216:219], v148 offset:0
	ds_read_b128 v[220:223], v148 offset:8192
	v_exp_f32_e32 v86, v86
	v_exp_f32_e32 v87, v87
	v_cvt_pk_bf16_f32 v99, v102, v103
	v_add_f32_e32 v251, v80, v82
	s_waitcnt lgkmcnt(4)
	v_mfma_f32_32x32x16_bf16 v[224:239], v[240:243], v[132:135], v[224:239]
	v_exp_f32_e32 v88, v88
	v_exp_f32_e32 v89, v89
	v_add_f32_e32 v253, v81, v83
	v_mfma_f32_32x32x16_bf16 v[64:79], v[244:247], v[132:135], v[64:79]
	ds_read_b128 v[240:243], v149 offset:0
	ds_read_b128 v[244:247], v149 offset:8192
	v_exp_f32_e32 v90, v90
	v_exp_f32_e32 v91, v91
	v_add_f32_e32 v251, v251, v84
	s_waitcnt lgkmcnt(4)
	v_mfma_f32_32x32x16_bf16 v[224:239], v[208:211], v[128:131], v[224:239]
	v_exp_f32_e32 v92, v92
	v_exp_f32_e32 v93, v93
	v_add_f32_e32 v253, v253, v85
	v_cvt_pk_bf16_f32 v100, v104, v105
	v_mfma_f32_32x32x16_bf16 v[64:79], v[212:215], v[128:131], v[64:79]
	ds_read_b128 v[208:211], v150 offset:0
	ds_read_b128 v[212:215], v150 offset:8192
	v_exp_f32_e32 v94, v94
	v_exp_f32_e32 v95, v95
	v_add_f32_e32 v251, v251, v86
	v_cvt_pk_bf16_f32 v101, v106, v107
	s_waitcnt lgkmcnt(4)
	v_mfma_f32_32x32x16_bf16 v[224:239], v[216:219], v[124:127], v[224:239]
	v_add_f32_e32 v253, v253, v87
	v_cvt_pk_bf16_f32 v102, v108, v109
	v_cvt_pk_bf16_f32 v103, v110, v111
	v_add_f32_e32 v251, v251, v88
	v_mfma_f32_32x32x16_bf16 v[64:79], v[220:223], v[124:127], v[64:79]
	ds_read_b128 v[216:219], v151 offset:0
	ds_read_b128 v[220:223], v151 offset:8192
	v_add_f32_e32 v253, v253, v89
	v_cvt_pk_bf16_f32 v104, v80, v81
	v_cvt_pk_bf16_f32 v105, v82, v83
	s_waitcnt lgkmcnt(4)
; #define SBAR() __builtin_amdgcn_sched_barrier(0)
; template <int D0> __device__ __forceinline__ void pv_one(f32x16& od, int vb, bf16x8 pa0, bf16x8 pa1, bf16x8 pa2, bf16x8 pa3) {
;   const s16x4 l0 = tr_read<v_rd_off(D0, 0, 0)>(vb), h0 = tr_read<v_rd_off(D0, 0, 1)>(vb), l1 = tr_read<v_rd_off(D0, 1, 0)>(vb), h1 = tr_read<v_rd_off(D0, 1, 1)>(vb);
;   const s16x4 l2 = tr_read<v_rd_off(D0, 2, 0)>(vb), h2 = tr_read<v_rd_off(D0, 2, 1)>(vb), l3 = tr_read<v_rd_off(D0, 3, 0)>(vb), h3 = tr_read<v_rd_off(D0, 3, 1)>(vb);
;   asm volatile("s_waitcnt lgkmcnt(0)" ::: "memory"); SBAR();
;     ...
;   od = __builtin_amdgcn_mfma_f32_32x32x16_bf16(pa0, PK(l0, h0), od, 0, 0, 0);
;   od = __builtin_amdgcn_mfma_f32_32x32x16_bf16(pa1, PK(l1, h1), od, 0, 0, 0);
;   od = __builtin_amdgcn_mfma_f32_32x32x16_bf16(pa2, PK(l2, h2), od, 0, 0, 0);
;   od = __builtin_amdgcn_mfma_f32_32x32x16_bf16(pa3, PK(l3, h3), od, 0, 0, 0);
;     ...
; }
; __device__ __forceinline__ void pv_d0(f32x16* o, int vb, bf16x8 pa0, bf16x8 pa1, bf16x8 pa2, bf16x8 pa3) {
;   pv_one<0>(o[0], vb, pa0, pa1, pa2, pa3); pv_one<1>(o[1], vb, pa0, pa1, pa2, pa3); pv_one<2>(o[2], vb, pa0, pa1, pa2, pa3); pv_one<3>(o[3], vb, pa0, pa1, pa2, pa3);
; template <typename TQ>
; __device__ __forceinline__ void attn_dense_body(const TQ* __restrict__ Qb, const bf16* __restrict__ Kh, const bf16* __restrict__ Vh,
;                                                 bf16* __restrict__ Ob, int seq, char* lds) {
;     ...
;   for (int j = 1; j + 1 < NT; j += 2) {
;     SBAR(); qkt(pB0, pB1, (bf16*)((char*)K_lds + cur * (int)SHM_K), qr, r32, hi);
;     finishSM(pA0, pA1, alA, l_reg, pa0, pa1, pa2, pa3); SBAR();
;     SWAIT(); SWRITE(next, SE);
;     if (j + 2 < NT) SLOAD(SO, (j + 2) * KVBLK); SBAR();
;     pv_d0(o, vb0 + prev * (int)SHM_V, pa0, pa1, pa2, pa3); partialSM_fix(pB0);
;     __syncthreads();
;     { const int t_ = prev; prev = cur; cur = next; next = t_; }
;     SBAR(); qkt(pA0, pA1, (bf16*)((char*)K_lds + cur * (int)SHM_K), qr, r32, hi);
;     finishSM(pB0, pB1, alB, l_reg, pa0, pa1, pa2, pa3); SBAR();
;     if (j + 2 < NT) { SWAIT(); SWRITE(next, SO); }
;     if (j + 3 < NT) SLOAD(SE, (j + 3) * KVBLK); SBAR();
;     pv_d0(o, vb0 + prev * (int)SHM_V, pa0, pa1, pa2, pa3); partialSM_fix(pA0);
;     __syncthreads();
;     { const int t_ = prev; prev = cur; cur = next; next = t_; }
;   }
	v_mfma_f32_32x32x16_bf16 v[224:239], v[240:243], v[120:123], v[224:239]
	v_add_f32_e32 v251, v251, v90
	v_cvt_pk_bf16_f32 v106, v84, v85
	v_cvt_pk_bf16_f32 v107, v86, v87
	v_mfma_f32_32x32x16_bf16 v[64:79], v[244:247], v[120:123], v[64:79]
	ds_read_b64_tr_b16 v[240:241], v179 offset:32768
	ds_read_b64_tr_b16 v[242:243], v179 offset:34816
	ds_read_b64_tr_b16 v[244:245], v179 offset:36864
	ds_read_b64_tr_b16 v[246:247], v179 offset:38912
	v_add_f32_e32 v253, v253, v91
	v_add_f32_e32 v251, v251, v92
	v_cvt_pk_bf16_f32 v108, v88, v89
	v_cvt_pk_bf16_f32 v109, v90, v91
	s_waitcnt lgkmcnt(6)
	v_mfma_f32_32x32x16_bf16 v[224:239], v[208:211], v[116:119], v[224:239]
	v_add_f32_e32 v253, v253, v93
	v_add_f32_e32 v251, v251, v94
	v_mfma_f32_32x32x16_bf16 v[64:79], v[212:215], v[116:119], v[64:79]
	ds_read_b64_tr_b16 v[208:209], v179 offset:40960
	ds_read_b64_tr_b16 v[210:211], v179 offset:43008
	ds_read_b64_tr_b16 v[212:213], v179 offset:45056
	ds_read_b64_tr_b16 v[214:215], v179 offset:47104
	v_add_f32_e32 v253, v253, v95
	v_cvt_pk_bf16_f32 v110, v92, v93
	v_cvt_pk_bf16_f32 v111, v94, v95
	s_waitcnt lgkmcnt(8)
	v_mfma_f32_32x32x16_bf16 v[224:239], v[216:219], v[112:115], v[224:239]
	v_add_f32_e32 v251, v251, v253
	v_add_f32_e32 v254, v254, v251
	v_mfma_f32_32x32x16_bf16 v[64:79], v[220:223], v[112:115], v[64:79]
	ds_read_b64_tr_b16 v[216:217], v179 offset:33280
	ds_read_b64_tr_b16 v[218:219], v179 offset:35328
	ds_read_b64_tr_b16 v[220:221], v179 offset:37376
	ds_read_b64_tr_b16 v[222:223], v179 offset:39424
	v_add_f32_e32 v169, v169, v254
	s_waitcnt lgkmcnt(8)
	v_mfma_f32_32x32x16_bf16 v[0:15], v[96:99], v[240:243], v[0:15]
	ds_read_b64_tr_b16 v[80:81], v179 offset:41472
	ds_read_b64_tr_b16 v[82:83], v179 offset:43520
	v_mfma_f32_32x32x16_bf16 v[0:15], v[100:103], v[244:247], v[0:15]
	ds_read_b64_tr_b16 v[84:85], v179 offset:45568
	ds_read_b64_tr_b16 v[86:87], v179 offset:47616
	v_exp_f32_e32 v224, v224
	v_exp_f32_e32 v225, v225
	s_waitcnt lgkmcnt(8)
	v_mfma_f32_32x32x16_bf16 v[0:15], v[104:107], v[208:211], v[0:15]
	ds_read_b64_tr_b16 v[88:89], v179 offset:33792
	ds_read_b64_tr_b16 v[90:91], v179 offset:35840
	v_exp_f32_e32 v226, v226
	v_exp_f32_e32 v227, v227
	v_mfma_f32_32x32x16_bf16 v[0:15], v[108:111], v[212:215], v[0:15]
	ds_read_b64_tr_b16 v[92:93], v179 offset:37888
	ds_read_b64_tr_b16 v[94:95], v179 offset:39936
	v_exp_f32_e32 v228, v228
	v_exp_f32_e32 v229, v229
	v_add_f32_e32 v254, v224, v226
	s_waitcnt lgkmcnt(8)
	v_mfma_f32_32x32x16_bf16 v[16:31], v[96:99], v[216:219], v[16:31]
	ds_read_b64_tr_b16 v[240:241], v179 offset:41984
	ds_read_b64_tr_b16 v[242:243], v179 offset:44032
	v_exp_f32_e32 v230, v230
	v_exp_f32_e32 v231, v231
	v_add_f32_e32 v255, v225, v227
	v_mfma_f32_32x32x16_bf16 v[16:31], v[100:103], v[220:223], v[16:31]
	ds_read_b64_tr_b16 v[244:245], v179 offset:46080
	ds_read_b64_tr_b16 v[246:247], v179 offset:48128
	v_exp_f32_e32 v232, v232
	v_exp_f32_e32 v233, v233
	v_add_f32_e32 v254, v254, v228
	s_waitcnt lgkmcnt(8)
	v_mfma_f32_32x32x16_bf16 v[16:31], v[104:107], v[80:83], v[16:31]
	ds_read_b64_tr_b16 v[80:81], v179 offset:34304
	ds_read_b64_tr_b16 v[82:83], v179 offset:36352
	v_exp_f32_e32 v234, v234
	v_exp_f32_e32 v235, v235
	v_add_f32_e32 v255, v255, v229
	v_mfma_f32_32x32x16_bf16 v[16:31], v[108:111], v[84:87], v[16:31]
	ds_read_b64_tr_b16 v[84:85], v179 offset:38400
	ds_read_b64_tr_b16 v[86:87], v179 offset:40448
	v_exp_f32_e32 v236, v236
	v_exp_f32_e32 v237, v237
	v_add_f32_e32 v254, v254, v230
	s_waitcnt lgkmcnt(8)
	v_mfma_f32_32x32x16_bf16 v[32:47], v[96:99], v[88:91], v[32:47]
	ds_read_b64_tr_b16 v[88:89], v179 offset:42496
	ds_read_b64_tr_b16 v[90:91], v179 offset:44544
	v_exp_f32_e32 v238, v238
	v_exp_f32_e32 v239, v239
	v_add_f32_e32 v255, v255, v231
	v_mfma_f32_32x32x16_bf16 v[32:47], v[100:103], v[92:95], v[32:47]
	ds_read_b64_tr_b16 v[92:93], v179 offset:46592
	ds_read_b64_tr_b16 v[94:95], v179 offset:48640
	v_add_f32_e32 v254, v254, v232
	v_add_f32_e32 v255, v255, v233
	v_add_f32_e32 v254, v254, v234
	s_waitcnt lgkmcnt(8)
	v_mfma_f32_32x32x16_bf16 v[32:47], v[104:107], v[240:243], v[32:47]
	v_add_f32_e32 v255, v255, v235
	v_add_f32_e32 v254, v254, v236
	v_add_f32_e32 v255, v255, v237
	v_mfma_f32_32x32x16_bf16 v[32:47], v[108:111], v[244:247], v[32:47]
	v_add_f32_e32 v254, v254, v238
	v_add_f32_e32 v255, v255, v239
	s_waitcnt vmcnt(2)
	s_waitcnt lgkmcnt(0)
	s_barrier
	ds_read_b128 v[208:211], v144 offset:16384
	ds_read_b128 v[212:215], v144 offset:24576
	ds_read_b128 v[216:219], v145 offset:16384
	ds_read_b128 v[220:223], v145 offset:24576
	ds_read_b128 v[240:243], v146 offset:16384
	ds_read_b128 v[244:247], v146 offset:24576
	v_mfma_f32_32x32x16_bf16 v[48:63], v[96:99], v[80:83], v[48:63]
	v_add_f32_e32 v254, v254, v255
	s_add_i32 m0, s82, 0x8000
	s_add_u32 s98, s92, 0x4000
	global_load_lds_dwordx4 v174, s[92:93]
	s_addc_u32 s99, s93, 0
	v_mfma_f32_32x32x16_bf16 v[48:63], v[100:103], v[84:87], v[48:63]
	s_add_i32 m0, s83, 0x8000
	s_nop 0
	global_load_lds_dwordx4 v175, s[92:93]
	s_mov_b64 s[92:93], s[98:99]
	v_mfma_f32_32x32x16_bf16 v[48:63], v[104:107], v[88:91], v[48:63]
	s_add_i32 m0, s80, 0x8000
	s_add_u32 s96, s90, 0x80
	s_addc_u32 s97, s91, 0
	global_load_lds_dwordx4 v249, s[90:91]
	v_mfma_f32_32x32x16_bf16 v[48:63], v[108:111], v[92:95], v[48:63]
	s_add_i32 m0, s81, 0x8000
	s_add_u32 s90, s90, 0x4000
	global_load_lds_dwordx4 v249, s[96:97]
	s_addc_u32 s91, s91, 0
	s_add_i32 s55, s55, 2
	s_cmp_ge_u32 s55, s32
	s_cbranch_scc1 .Latt_exit_2
	s_branch .Latt_loop

; #define SBAR() __builtin_amdgcn_sched_barrier(0)
; __device__ __forceinline__ void partialSM_fix(f32x16& p0) { for (int r = 0; r < 16; ++r) p0[r] = __builtin_amdgcn_exp2f(p0[r]); }
; __device__ __forceinline__ void finishSM(f32x16& p0, f32x16& p1, float alpha, float& l_reg, bf16x8& pa0, bf16x8& pa1, bf16x8& pa2, bf16x8& pa3) {
;     ...
;   { auto rr = __builtin_amdgcn_permlane32_swap(__float_as_uint(ps), __float_as_uint(ps), false, false);
;     ps = __uint_as_float(rr[0]) + __uint_as_float(rr[1]); }
;   l_reg = l_reg * alpha + ps;
; template <typename TQ>
; __device__ __forceinline__ void attn_dense_body(const TQ* __restrict__ Qb, const bf16* __restrict__ Kh, const bf16* __restrict__ Vh,
;                                                 bf16* __restrict__ Ob, int seq, char* lds) {
;     ...
;   SBAR(); qkt(pB0, pB1, (bf16*)((char*)K_lds + cur * (int)SHM_K), qr, r32, hi);
;   finishSM(pA0, pA1, alA, l_reg, pa0, pa1, pa2, pa3); SBAR();
;   pv_d0(o, vb0 + prev * (int)SHM_V, pa0, pa1, pa2, pa3); partialSM_fix(pB0);
;   finishSM(pB0, pB1, alB, l_reg, pa0, pa1, pa2, pa3); SBAR();
;   pv_d0(o, vb0 + cur * (int)SHM_V, pa0, pa1, pa2, pa3);
.Latt_exit:
	s_waitcnt lgkmcnt(0)
	s_waitcnt vmcnt(0)
	s_barrier
	v_mov_b32_e32 v223, v224
	v_mov_b32_e32 v221, v226
	v_mov_b32_e32 v224, v227
	v_mov_b32_e32 v220, v228
	v_mov_b32_e32 v222, v229
	v_mov_b32_e32 v218, v230
	v_mov_b32_e32 v219, v231
	v_mov_b32_e32 v215, v232
	v_mov_b32_e32 v217, v233
	v_mov_b32_e32 v214, v234
	v_mov_b32_e32 v216, v235
	v_mov_b32_e32 v211, v236
	v_mov_b32_e32 v213, v237
	v_mov_b32_e32 v209, v238
	v_mov_b32_e32 v212, v239
	v_mov_b32_e32 v248, v169
	v_mov_b32_e32 v249, v169
	v_add_u32_e32 v207, s20, v179
	s_nop 1
	v_permlane32_swap_b32_e32 v248, v249
	v_add_f32_e32 v248, v248, v249
	v_mov_b32_e32 v169, v248
	s_branch .LBB0_1098
